# mLSTM chunk scan: per-chunk a/g scalars fetched by two lane-indexed loads up front (v_readlane per chunk) instead of a dependent global load pair per iteration
# baseline (speedup 1.0000x reference)
.LBB0_366:
	s_and_saveexec_b64 s[10:11], vcc
	s_cbranch_execz .LBB0_365
	s_and_b32 s13, s19, 7
	s_mul_i32 s8, s13, 0x480
	v_add_u32_e32 v0, s8, v186
	s_ashr_i32 s8, s19, 5
	s_ashr_i32 s9, s8, 31
	v_readlane_b32 s44, v251, 4
	s_and_b32 s12, s18, 0xffffffe0
	s_lshl_b64 s[8:9], s[8:9], 23
	v_readlane_b32 s58, v251, 18
	v_readlane_b32 s59, v251, 19
	s_add_u32 s8, s58, s8
	s_addc_u32 s9, s59, s9
	s_and_b32 s14, s18, 0x60
	v_ashrrev_i32_e32 v1, 31, v0
	v_lshl_add_u64 v[0:1], v[0:1], 2, s[8:9]
	s_mul_i32 s90, s14, 0x9000
	s_waitcnt lgkmcnt(0)
	v_lshl_add_u64 v[4:5], v[0:1], 0, s[90:91]
	s_mov_b32 s8, 0x9000
	v_add_co_u32_e64 v10, s[8:9], s8, v4
	global_load_dword v7, v[4:5], off
	global_load_dword v6, v[4:5], off offset:1536
	global_load_dword v8, v[4:5], off offset:3072
	v_addc_co_u32_e64 v11, s[8:9], 0, v5, s[8:9]
	s_mov_b32 s8, 0x12000
	global_load_dword v98, v[10:11], off
	global_load_dword v97, v[10:11], off offset:1536
	global_load_dword v96, v[10:11], off offset:3072
	v_add_co_u32_e64 v10, s[8:9], s8, v4
	s_cmp_eq_u32 s13, 0
	s_nop 0
	v_addc_co_u32_e64 v11, s[8:9], 0, v5, s[8:9]
	s_mov_b32 s8, 0x1b000
	global_load_dword v95, v[10:11], off
	global_load_dword v94, v[10:11], off offset:1536
	global_load_dword v93, v[10:11], off offset:3072
	v_add_co_u32_e64 v10, s[8:9], s8, v4
	v_readlane_b32 s25, v251, 51
	s_nop 0
	v_addc_co_u32_e64 v11, s[8:9], 0, v5, s[8:9]
	s_mov_b32 s8, 0x24000
	global_load_dword v92, v[10:11], off
	global_load_dword v91, v[10:11], off offset:1536
	global_load_dword v90, v[10:11], off offset:3072
	v_add_co_u32_e64 v10, s[8:9], s8, v4
	v_readlane_b32 s36, v251, 52
	s_nop 0
	v_addc_co_u32_e64 v11, s[8:9], 0, v5, s[8:9]
	s_mov_b32 s8, 0x2d000
	global_load_dword v89, v[10:11], off
	global_load_dword v88, v[10:11], off offset:1536
	global_load_dword v87, v[10:11], off offset:3072
	v_add_co_u32_e64 v10, s[8:9], s8, v4
	v_readlane_b32 s40, v251, 54
	s_nop 0
	v_addc_co_u32_e64 v11, s[8:9], 0, v5, s[8:9]
	s_mov_b32 s8, 0x36000
	global_load_dword v86, v[10:11], off
	global_load_dword v85, v[10:11], off offset:1536
	global_load_dword v84, v[10:11], off offset:3072
	v_add_co_u32_e64 v10, s[8:9], s8, v4
	v_readlane_b32 s37, v251, 53
	s_nop 0
	v_addc_co_u32_e64 v11, s[8:9], 0, v5, s[8:9]
	s_mov_b32 s8, 0x3f000
	global_load_dword v83, v[10:11], off
	global_load_dword v82, v[10:11], off offset:1536
	global_load_dword v81, v[10:11], off offset:3072
	v_add_co_u32_e64 v10, s[8:9], s8, v4
	v_readlane_b32 s45, v251, 5
	s_nop 0
	v_addc_co_u32_e64 v11, s[8:9], 0, v5, s[8:9]
	s_mov_b32 s8, 0x48000
	global_load_dword v80, v[10:11], off
	global_load_dword v79, v[10:11], off offset:1536
	global_load_dword v78, v[10:11], off offset:3072
	v_add_co_u32_e64 v10, s[8:9], s8, v4
	v_readlane_b32 s46, v251, 6
	s_nop 0
	v_addc_co_u32_e64 v11, s[8:9], 0, v5, s[8:9]
	s_mov_b32 s8, 0x51000
	global_load_dword v77, v[10:11], off
	global_load_dword v76, v[10:11], off offset:1536
	global_load_dword v75, v[10:11], off offset:3072
	v_add_co_u32_e64 v10, s[8:9], s8, v4
	v_readlane_b32 s47, v251, 7
	s_nop 0
	v_addc_co_u32_e64 v11, s[8:9], 0, v5, s[8:9]
	s_mov_b32 s8, 0x5a000
	global_load_dword v74, v[10:11], off
	global_load_dword v73, v[10:11], off offset:1536
	global_load_dword v72, v[10:11], off offset:3072
	v_add_co_u32_e64 v10, s[8:9], s8, v4
	v_readlane_b32 s48, v251, 8
	s_nop 0
	v_addc_co_u32_e64 v11, s[8:9], 0, v5, s[8:9]
	s_mov_b32 s8, 0x63000
	global_load_dword v71, v[10:11], off
	global_load_dword v70, v[10:11], off offset:1536
	global_load_dword v69, v[10:11], off offset:3072
	v_add_co_u32_e64 v10, s[8:9], s8, v4
	v_readlane_b32 s49, v251, 9
	s_nop 0
	v_addc_co_u32_e64 v11, s[8:9], 0, v5, s[8:9]
	s_mov_b32 s8, 0x6c000
	global_load_dword v68, v[10:11], off
	global_load_dword v67, v[10:11], off offset:1536
	global_load_dword v66, v[10:11], off offset:3072
	v_add_co_u32_e64 v10, s[8:9], s8, v4
	v_readlane_b32 s50, v251, 10
	s_nop 0
	v_addc_co_u32_e64 v11, s[8:9], 0, v5, s[8:9]
	s_mov_b32 s8, 0x75000
	global_load_dword v65, v[10:11], off
	global_load_dword v64, v[10:11], off offset:1536
	global_load_dword v63, v[10:11], off offset:3072
	v_add_co_u32_e64 v10, s[8:9], s8, v4
	v_readlane_b32 s51, v251, 11
	s_nop 0
	v_addc_co_u32_e64 v11, s[8:9], 0, v5, s[8:9]
	s_mov_b32 s8, 0x7e000
	global_load_dword v62, v[10:11], off
	global_load_dword v61, v[10:11], off offset:1536
	global_load_dword v60, v[10:11], off offset:3072
	v_add_co_u32_e64 v10, s[8:9], s8, v4
	v_readlane_b32 s52, v251, 12
	s_nop 0
	v_addc_co_u32_e64 v11, s[8:9], 0, v5, s[8:9]
	s_mov_b32 s8, 0x87000
	global_load_dword v59, v[10:11], off
	global_load_dword v58, v[10:11], off offset:1536
	global_load_dword v57, v[10:11], off offset:3072
	v_add_co_u32_e64 v10, s[8:9], s8, v4
	v_readlane_b32 s53, v251, 13
	s_nop 0
	v_addc_co_u32_e64 v11, s[8:9], 0, v5, s[8:9]
	s_mov_b32 s8, 0x90000
	global_load_dword v56, v[10:11], off
	global_load_dword v55, v[10:11], off offset:1536
	global_load_dword v54, v[10:11], off offset:3072
	v_add_co_u32_e64 v10, s[8:9], s8, v4
	v_readlane_b32 s54, v251, 14
	s_nop 0
	v_addc_co_u32_e64 v11, s[8:9], 0, v5, s[8:9]
	s_mov_b32 s8, 0x99000
	global_load_dword v53, v[10:11], off
	global_load_dword v52, v[10:11], off offset:1536
	global_load_dword v51, v[10:11], off offset:3072
	v_add_co_u32_e64 v10, s[8:9], s8, v4
	v_readlane_b32 s55, v251, 15
	s_nop 0
	v_addc_co_u32_e64 v11, s[8:9], 0, v5, s[8:9]
	s_mov_b32 s8, 0xa2000
	global_load_dword v50, v[10:11], off
	global_load_dword v49, v[10:11], off offset:1536
	global_load_dword v48, v[10:11], off offset:3072
	v_add_co_u32_e64 v10, s[8:9], s8, v4
	v_readlane_b32 s56, v251, 16
	s_nop 0
	v_addc_co_u32_e64 v11, s[8:9], 0, v5, s[8:9]
	s_mov_b32 s8, 0xab000
	global_load_dword v47, v[10:11], off
	global_load_dword v46, v[10:11], off offset:1536
	global_load_dword v45, v[10:11], off offset:3072
	v_add_co_u32_e64 v10, s[8:9], s8, v4
	v_readlane_b32 s57, v251, 17
	s_nop 0
	v_addc_co_u32_e64 v11, s[8:9], 0, v5, s[8:9]
	s_mov_b32 s8, 0xb4000
	global_load_dword v44, v[10:11], off
	global_load_dword v43, v[10:11], off offset:1536
	global_load_dword v42, v[10:11], off offset:3072
	v_add_co_u32_e64 v10, s[8:9], s8, v4
	s_nop 1
	v_addc_co_u32_e64 v11, s[8:9], 0, v5, s[8:9]
	s_mov_b32 s8, 0xbd000
	global_load_dword v41, v[10:11], off
	global_load_dword v40, v[10:11], off offset:1536
	global_load_dword v39, v[10:11], off offset:3072
	v_add_co_u32_e64 v10, s[8:9], s8, v4
	s_nop 1
	v_addc_co_u32_e64 v11, s[8:9], 0, v5, s[8:9]
	s_mov_b32 s8, 0xc6000
	global_load_dword v38, v[10:11], off
	global_load_dword v37, v[10:11], off offset:1536
	global_load_dword v36, v[10:11], off offset:3072
	v_add_co_u32_e64 v10, s[8:9], s8, v4
	s_nop 1
	v_addc_co_u32_e64 v11, s[8:9], 0, v5, s[8:9]
	s_mov_b32 s8, 0xcf000
	global_load_dword v35, v[10:11], off
	global_load_dword v34, v[10:11], off offset:1536
	global_load_dword v33, v[10:11], off offset:3072
	v_add_co_u32_e64 v10, s[8:9], s8, v4
	s_nop 1
	v_addc_co_u32_e64 v11, s[8:9], 0, v5, s[8:9]
	s_mov_b32 s8, 0xd8000
	global_load_dword v32, v[10:11], off
	global_load_dword v31, v[10:11], off offset:1536
	global_load_dword v30, v[10:11], off offset:3072
	v_add_co_u32_e64 v10, s[8:9], s8, v4
	s_nop 1
	v_addc_co_u32_e64 v11, s[8:9], 0, v5, s[8:9]
	s_mov_b32 s8, 0xe1000
	global_load_dword v29, v[10:11], off
	global_load_dword v28, v[10:11], off offset:1536
	global_load_dword v27, v[10:11], off offset:3072
	v_add_co_u32_e64 v10, s[8:9], s8, v4
	s_nop 1
	v_addc_co_u32_e64 v11, s[8:9], 0, v5, s[8:9]
	s_mov_b32 s8, 0xea000
	global_load_dword v26, v[10:11], off
	global_load_dword v25, v[10:11], off offset:1536
	global_load_dword v24, v[10:11], off offset:3072
	v_add_co_u32_e64 v10, s[8:9], s8, v4
	s_nop 1
	v_addc_co_u32_e64 v11, s[8:9], 0, v5, s[8:9]
	s_mov_b32 s8, 0xf3000
	global_load_dword v23, v[10:11], off
	global_load_dword v22, v[10:11], off offset:1536
	global_load_dword v21, v[10:11], off offset:3072
	v_add_co_u32_e64 v10, s[8:9], s8, v4
	s_nop 1
	v_addc_co_u32_e64 v11, s[8:9], 0, v5, s[8:9]
	s_mov_b32 s8, 0xfc000
	s_nop 0
	v_add_co_u32_e64 v12, s[8:9], s8, v4
	global_load_dword v20, v[10:11], off
	global_load_dword v19, v[10:11], off offset:1536
	global_load_dword v18, v[10:11], off offset:3072
	v_addc_co_u32_e64 v13, s[8:9], 0, v5, s[8:9]
	s_mov_b32 s8, 0x105000
	global_load_dword v17, v[12:13], off
	global_load_dword v11, v[12:13], off offset:1536
	global_load_dword v10, v[12:13], off offset:3072
	v_add_co_u32_e64 v12, s[8:9], s8, v4
	s_nop 1
	v_addc_co_u32_e64 v13, s[8:9], 0, v5, s[8:9]
	s_mov_b32 s8, 0x10e000
	s_nop 0
	v_add_co_u32_e64 v100, s[8:9], s8, v4
	global_load_dword v16, v[12:13], off
	global_load_dword v15, v[12:13], off offset:1536
	global_load_dword v14, v[12:13], off offset:3072
	v_addc_co_u32_e64 v101, s[8:9], 0, v5, s[8:9]
	s_cselect_b64 s[8:9], -1, 0
	s_ashr_i32 s13, s12, 31
	s_lshl_b64 s[14:15], s[12:13], 2
	s_add_u32 s16, s67, s14
	s_addc_u32 s17, s25, s15
	global_load_dword v13, v[100:101], off
	global_load_dword v12, v[100:101], off offset:1536
	global_load_dword v3, v[100:101], off offset:3072
	global_load_dword v9, v181, s[16:17]
	s_add_u32 s16, s34, s14
	s_addc_u32 s17, s36, s15
	global_load_dword v99, v181, s[16:17]
	v_lshlrev_b32_e32 v202, 2, v216
	s_add_u32 s16, s67, s14
	s_addc_u32 s17, s25, s15
	global_load_dword v200, v202, s[16:17]
	s_add_u32 s16, s34, s14
	s_addc_u32 s17, s36, s15
	global_load_dword v201, v202, s[16:17]
	s_and_b64 s[8:9], s[8:9], s[6:7]
	global_store_dword v[4:5], v181, off
	global_store_dword v[4:5], v181, off offset:1536
	global_store_dword v[4:5], v181, off offset:3072
	s_and_saveexec_b64 s[16:17], s[8:9]
	s_cbranch_execz .LBB0_369
	s_add_u32 s14, s37, s14
	s_addc_u32 s15, s40, s15
	global_store_dword v181, v181, s[14:15]
.LBB0_369:
	s_or_b64 exec, exec, s[16:17]
	s_waitcnt vmcnt(0)
	v_add_f32_e32 v4, 0, v99
	v_max_f32_e32 v5, v9, v9
	v_max_f32_e32 v99, v4, v5
	v_sub_f32_e32 v4, v4, v99
	v_mul_f32_e32 v4, 0x3fb8aa3b, v4
	v_sub_f32_e32 v5, v9, v99
	v_exp_f32_e32 v4, v4
	v_mul_f32_e32 v5, 0x3fb8aa3b, v5
	v_exp_f32_e32 v100, v5
	s_or_b32 s16, s12, 1
	s_ashr_i32 s17, s16, 31
	s_lshl_b64 s[14:15], s[16:17], 2
	v_mul_f32_e32 v102, 0, v4
	v_lshlrev_b32_e32 v104, 16, v6
	v_and_b32_e32 v105, 0xffff0000, v6
	s_add_u32 s26, s67, s14
	v_lshlrev_b32_e32 v4, 16, v7
	v_and_b32_e32 v5, 0xffff0000, v7
	v_pk_fma_f32 v[6:7], v[100:101], v[104:105], v[102:103] op_sel_hi:[0,1,0]
	v_lshlrev_b32_e32 v104, 16, v8
	v_and_b32_e32 v105, 0xffff0000, v8
	s_addc_u32 s27, s25, s15
	v_pk_fma_f32 v[4:5], v[100:101], v[4:5], v[102:103] op_sel_hi:[0,1,0]
	v_pk_fma_f32 v[8:9], v[100:101], v[104:105], v[102:103] op_sel_hi:[0,1,0]
	v_readlane_b32 s100, v200, 1
	s_add_u32 s26, s34, s14
	s_addc_u32 s27, s36, s15
	v_readlane_b32 s101, v201, 1
	s_nop 1
	v_mov_b32_e32 v100, s100
	v_mov_b32_e32 v101, s101
	s_and_b32 s13, s16, 0x61
	s_mul_i32 s90, s13, 0x9000
	v_lshl_add_u64 v[102:103], v[0:1], 0, s[90:91]
	v_cvt_pk_bf16_f32 v104, v4, v5
	global_store_dword v[102:103], v104, off
	v_cvt_pk_bf16_f32 v104, v6, v7
	global_store_dword v[102:103], v104, off offset:1536
	v_cvt_pk_bf16_f32 v104, v8, v9
	global_store_dword v[102:103], v104, off offset:3072
	s_and_saveexec_b64 s[16:17], s[8:9]
	s_cbranch_execz .LBB0_371
	s_add_u32 s14, s37, s14
	s_addc_u32 s15, s40, s15
	global_store_dword v181, v99, s[14:15]
.LBB0_371:
	s_or_b64 exec, exec, s[16:17]
	s_nop 0
	v_add_f32_e32 v101, v99, v101
	v_max_f32_e32 v99, v100, v100
	v_max_f32_e32 v99, v101, v99
	v_sub_f32_e32 v101, v101, v99
	v_mul_f32_e32 v101, 0x3fb8aa3b, v101
	v_sub_f32_e32 v100, v100, v99
	v_exp_f32_e32 v102, v101
	v_mul_f32_e32 v100, 0x3fb8aa3b, v100
	s_or_b32 s16, s12, 2
	v_exp_f32_e32 v100, v100
	s_ashr_i32 s17, s16, 31
	s_lshl_b64 s[14:15], s[16:17], 2
	s_add_u32 s26, s67, s14
	v_lshlrev_b32_e32 v104, 16, v98
	v_pk_mul_f32 v[4:5], v[4:5], v[102:103] op_sel_hi:[1,0]
	v_and_b32_e32 v105, 0xffff0000, v98
	s_addc_u32 s27, s25, s15
	v_pk_fma_f32 v[4:5], v[100:101], v[104:105], v[4:5] op_sel_hi:[0,1,1]
	v_lshlrev_b32_e32 v104, 16, v97
	v_and_b32_e32 v105, 0xffff0000, v97
	v_readlane_b32 s100, v200, 2
	s_add_u32 s26, s34, s14
	v_pk_mul_f32 v[6:7], v[6:7], v[102:103] op_sel_hi:[1,0]
	s_addc_u32 s27, s36, s15
	v_pk_fma_f32 v[6:7], v[100:101], v[104:105], v[6:7] op_sel_hi:[0,1,1]
	v_lshlrev_b32_e32 v104, 16, v96
	v_and_b32_e32 v105, 0xffff0000, v96
	v_readlane_b32 s101, v201, 2
	s_nop 1
	v_mov_b32_e32 v97, s100
	v_mov_b32_e32 v96, s101
	s_and_b32 s13, s16, 0x62
	v_pk_mul_f32 v[8:9], v[8:9], v[102:103] op_sel_hi:[1,0]
	s_mul_i32 s90, s13, 0x9000
	v_pk_fma_f32 v[8:9], v[100:101], v[104:105], v[8:9] op_sel_hi:[0,1,1]
	v_lshl_add_u64 v[100:101], v[0:1], 0, s[90:91]
	v_cvt_pk_bf16_f32 v98, v4, v5
	global_store_dword v[100:101], v98, off
	v_cvt_pk_bf16_f32 v98, v6, v7
	global_store_dword v[100:101], v98, off offset:1536
	v_cvt_pk_bf16_f32 v98, v8, v9
	global_store_dword v[100:101], v98, off offset:3072
	s_and_saveexec_b64 s[16:17], s[8:9]
	v_readlane_b32 s56, v254, 35
	v_readlane_b32 s57, v254, 36
	s_cbranch_execz .LBB0_373
	s_add_u32 s14, s37, s14
	s_addc_u32 s15, s40, s15
	global_store_dword v181, v99, s[14:15]
.LBB0_373:
	s_or_b64 exec, exec, s[16:17]
	s_nop 0
	v_add_f32_e32 v98, v99, v96
	v_max_f32_e32 v96, v97, v97
	v_max_f32_e32 v96, v98, v96
	v_sub_f32_e32 v98, v98, v96
	v_mul_f32_e32 v98, 0x3fb8aa3b, v98
	v_sub_f32_e32 v97, v97, v96
	v_exp_f32_e32 v98, v98
	v_mul_f32_e32 v97, 0x3fb8aa3b, v97
	v_exp_f32_e32 v100, v97
	s_or_b32 s16, s12, 3
	s_ashr_i32 s17, s16, 31
	s_lshl_b64 s[14:15], s[16:17], 2
	v_lshlrev_b32_e32 v102, 16, v95
	v_and_b32_e32 v103, 0xffff0000, v95
	v_pk_mul_f32 v[4:5], v[4:5], v[98:99] op_sel_hi:[1,0]
	s_add_u32 s26, s67, s14
	v_pk_fma_f32 v[4:5], v[100:101], v[102:103], v[4:5] op_sel_hi:[0,1,1]
	v_lshlrev_b32_e32 v102, 16, v94
	v_and_b32_e32 v103, 0xffff0000, v94
	v_lshlrev_b32_e32 v94, 16, v93
	v_and_b32_e32 v95, 0xffff0000, v93
	v_pk_mul_f32 v[8:9], v[8:9], v[98:99] op_sel_hi:[1,0]
	s_addc_u32 s27, s25, s15
	v_pk_fma_f32 v[8:9], v[100:101], v[94:95], v[8:9] op_sel_hi:[0,1,1]
	v_readlane_b32 s100, v200, 3
	s_add_u32 s26, s34, s14
	s_addc_u32 s27, s36, s15
	v_readlane_b32 s101, v201, 3
	s_nop 1
	v_mov_b32_e32 v94, s100
	v_mov_b32_e32 v93, s101
	s_and_b32 s13, s16, 0x63
	v_pk_mul_f32 v[6:7], v[6:7], v[98:99] op_sel_hi:[1,0]
	s_mul_i32 s90, s13, 0x9000
	v_pk_fma_f32 v[6:7], v[100:101], v[102:103], v[6:7] op_sel_hi:[0,1,1]
	v_lshl_add_u64 v[98:99], v[0:1], 0, s[90:91]
	v_cvt_pk_bf16_f32 v95, v4, v5
	global_store_dword v[98:99], v95, off
	v_cvt_pk_bf16_f32 v95, v6, v7
	global_store_dword v[98:99], v95, off offset:1536
	v_cvt_pk_bf16_f32 v95, v8, v9
	global_store_dword v[98:99], v95, off offset:3072
	s_and_saveexec_b64 s[16:17], s[8:9]
	s_cbranch_execz .LBB0_375
	s_add_u32 s14, s37, s14
	s_addc_u32 s15, s40, s15
	global_store_dword v181, v96, s[14:15]
.LBB0_375:
	s_or_b64 exec, exec, s[16:17]
	s_nop 0
	v_add_f32_e32 v95, v96, v93
	v_max_f32_e32 v93, v94, v94
	v_max_f32_e32 v93, v95, v93
	v_sub_f32_e32 v95, v95, v93
	v_mul_f32_e32 v95, 0x3fb8aa3b, v95
	v_sub_f32_e32 v94, v94, v93
	v_exp_f32_e32 v96, v95
	v_mul_f32_e32 v94, 0x3fb8aa3b, v94
	s_or_b32 s16, s12, 4
	v_exp_f32_e32 v94, v94
	s_ashr_i32 s17, s16, 31
	s_lshl_b64 s[14:15], s[16:17], 2
	s_add_u32 s26, s67, s14
	v_lshlrev_b32_e32 v98, 16, v92
	v_and_b32_e32 v99, 0xffff0000, v92
	v_pk_mul_f32 v[4:5], v[4:5], v[96:97] op_sel_hi:[1,0]
	s_addc_u32 s27, s25, s15
	v_pk_fma_f32 v[4:5], v[94:95], v[98:99], v[4:5] op_sel_hi:[0,1,1]
	v_lshlrev_b32_e32 v98, 16, v91
	v_and_b32_e32 v99, 0xffff0000, v91
	v_readlane_b32 s100, v200, 4
	s_add_u32 s26, s34, s14
	v_pk_mul_f32 v[6:7], v[6:7], v[96:97] op_sel_hi:[1,0]
	s_addc_u32 s27, s36, s15
	v_pk_fma_f32 v[6:7], v[94:95], v[98:99], v[6:7] op_sel_hi:[0,1,1]
	v_lshlrev_b32_e32 v98, 16, v90
	v_and_b32_e32 v99, 0xffff0000, v90
	v_readlane_b32 s101, v201, 4
	s_nop 1
	v_mov_b32_e32 v91, s100
	v_mov_b32_e32 v90, s101
	s_and_b32 s13, s16, 0x64
	v_pk_mul_f32 v[8:9], v[8:9], v[96:97] op_sel_hi:[1,0]
	s_mul_i32 s90, s13, 0x9000
	v_pk_fma_f32 v[8:9], v[94:95], v[98:99], v[8:9] op_sel_hi:[0,1,1]
	v_lshl_add_u64 v[94:95], v[0:1], 0, s[90:91]
	v_cvt_pk_bf16_f32 v92, v4, v5
	global_store_dword v[94:95], v92, off
	v_cvt_pk_bf16_f32 v92, v6, v7
	global_store_dword v[94:95], v92, off offset:1536
	v_cvt_pk_bf16_f32 v92, v8, v9
	global_store_dword v[94:95], v92, off offset:3072
	s_and_saveexec_b64 s[16:17], s[8:9]
	s_cbranch_execz .LBB0_377
	s_add_u32 s14, s37, s14
	s_addc_u32 s15, s40, s15
	global_store_dword v181, v93, s[14:15]
.LBB0_377:
	s_or_b64 exec, exec, s[16:17]
	s_nop 0
	v_add_f32_e32 v92, v93, v90
	v_max_f32_e32 v90, v91, v91
	v_max_f32_e32 v90, v92, v90
	v_sub_f32_e32 v92, v92, v90
	v_mul_f32_e32 v92, 0x3fb8aa3b, v92
	v_sub_f32_e32 v91, v91, v90
	v_exp_f32_e32 v92, v92
	v_mul_f32_e32 v91, 0x3fb8aa3b, v91
	v_exp_f32_e32 v94, v91
	s_or_b32 s16, s12, 5
	s_ashr_i32 s17, s16, 31
	s_lshl_b64 s[14:15], s[16:17], 2
	v_lshlrev_b32_e32 v96, 16, v89
	v_and_b32_e32 v97, 0xffff0000, v89
	v_pk_mul_f32 v[4:5], v[4:5], v[92:93] op_sel_hi:[1,0]
	s_add_u32 s26, s67, s14
	v_pk_fma_f32 v[4:5], v[94:95], v[96:97], v[4:5] op_sel_hi:[0,1,1]
	v_lshlrev_b32_e32 v96, 16, v88
	v_and_b32_e32 v97, 0xffff0000, v88
	v_lshlrev_b32_e32 v88, 16, v87
	v_and_b32_e32 v89, 0xffff0000, v87
	v_pk_mul_f32 v[8:9], v[8:9], v[92:93] op_sel_hi:[1,0]
	s_addc_u32 s27, s25, s15
	v_pk_fma_f32 v[8:9], v[94:95], v[88:89], v[8:9] op_sel_hi:[0,1,1]
	v_readlane_b32 s100, v200, 5
	s_add_u32 s26, s34, s14
	s_addc_u32 s27, s36, s15
	v_readlane_b32 s101, v201, 5
	s_nop 1
	v_mov_b32_e32 v88, s100
	v_mov_b32_e32 v87, s101
	s_and_b32 s13, s16, 0x65
	v_pk_mul_f32 v[6:7], v[6:7], v[92:93] op_sel_hi:[1,0]
	s_mul_i32 s90, s13, 0x9000
	v_pk_fma_f32 v[6:7], v[94:95], v[96:97], v[6:7] op_sel_hi:[0,1,1]
	v_lshl_add_u64 v[92:93], v[0:1], 0, s[90:91]
	v_cvt_pk_bf16_f32 v89, v4, v5
	global_store_dword v[92:93], v89, off
	v_cvt_pk_bf16_f32 v89, v6, v7
	global_store_dword v[92:93], v89, off offset:1536
	v_cvt_pk_bf16_f32 v89, v8, v9
	global_store_dword v[92:93], v89, off offset:3072
	s_and_saveexec_b64 s[16:17], s[8:9]
	s_cbranch_execz .LBB0_379
	s_add_u32 s14, s37, s14
	s_addc_u32 s15, s40, s15
	global_store_dword v181, v90, s[14:15]
.LBB0_379:
	s_or_b64 exec, exec, s[16:17]
	s_nop 0
	v_add_f32_e32 v89, v90, v87
	v_max_f32_e32 v87, v88, v88
	v_max_f32_e32 v87, v89, v87
	v_sub_f32_e32 v89, v89, v87
	v_mul_f32_e32 v89, 0x3fb8aa3b, v89
	v_sub_f32_e32 v88, v88, v87
	v_exp_f32_e32 v90, v89
	v_mul_f32_e32 v88, 0x3fb8aa3b, v88
	s_or_b32 s16, s12, 6
	v_exp_f32_e32 v88, v88
	s_ashr_i32 s17, s16, 31
	s_lshl_b64 s[14:15], s[16:17], 2
	s_add_u32 s26, s67, s14
	v_lshlrev_b32_e32 v92, 16, v86
	v_and_b32_e32 v93, 0xffff0000, v86
	v_pk_mul_f32 v[4:5], v[4:5], v[90:91] op_sel_hi:[1,0]
	s_addc_u32 s27, s25, s15
	v_pk_fma_f32 v[4:5], v[88:89], v[92:93], v[4:5] op_sel_hi:[0,1,1]
	v_lshlrev_b32_e32 v92, 16, v85
	v_and_b32_e32 v93, 0xffff0000, v85
	v_readlane_b32 s100, v200, 6
	s_add_u32 s26, s34, s14
	v_pk_mul_f32 v[6:7], v[6:7], v[90:91] op_sel_hi:[1,0]
	s_addc_u32 s27, s36, s15
	v_pk_fma_f32 v[6:7], v[88:89], v[92:93], v[6:7] op_sel_hi:[0,1,1]
	v_lshlrev_b32_e32 v92, 16, v84
	v_and_b32_e32 v93, 0xffff0000, v84
	v_readlane_b32 s101, v201, 6
	s_nop 1
	v_mov_b32_e32 v85, s100
	v_mov_b32_e32 v84, s101
	s_and_b32 s13, s16, 0x66
	v_pk_mul_f32 v[8:9], v[8:9], v[90:91] op_sel_hi:[1,0]
	s_mul_i32 s90, s13, 0x9000
	v_pk_fma_f32 v[8:9], v[88:89], v[92:93], v[8:9] op_sel_hi:[0,1,1]
	v_lshl_add_u64 v[88:89], v[0:1], 0, s[90:91]
	v_cvt_pk_bf16_f32 v86, v4, v5
	global_store_dword v[88:89], v86, off
	v_cvt_pk_bf16_f32 v86, v6, v7
	global_store_dword v[88:89], v86, off offset:1536
	v_cvt_pk_bf16_f32 v86, v8, v9
	global_store_dword v[88:89], v86, off offset:3072
	s_and_saveexec_b64 s[16:17], s[8:9]
	s_cbranch_execz .LBB0_381
	s_add_u32 s14, s37, s14
	s_addc_u32 s15, s40, s15
	global_store_dword v181, v87, s[14:15]
.LBB0_381:
	s_or_b64 exec, exec, s[16:17]
	s_nop 0
	v_add_f32_e32 v86, v87, v84
	v_max_f32_e32 v84, v85, v85
	v_max_f32_e32 v84, v86, v84
	v_sub_f32_e32 v86, v86, v84
	v_mul_f32_e32 v86, 0x3fb8aa3b, v86
	v_sub_f32_e32 v85, v85, v84
	v_exp_f32_e32 v86, v86
	v_mul_f32_e32 v85, 0x3fb8aa3b, v85
	v_exp_f32_e32 v88, v85
	s_or_b32 s16, s12, 7
	s_ashr_i32 s17, s16, 31
	s_lshl_b64 s[14:15], s[16:17], 2
	v_lshlrev_b32_e32 v90, 16, v83
	v_and_b32_e32 v91, 0xffff0000, v83
	v_pk_mul_f32 v[4:5], v[4:5], v[86:87] op_sel_hi:[1,0]
	s_add_u32 s26, s67, s14
	v_pk_fma_f32 v[4:5], v[88:89], v[90:91], v[4:5] op_sel_hi:[0,1,1]
	v_lshlrev_b32_e32 v90, 16, v82
	v_and_b32_e32 v91, 0xffff0000, v82
	v_lshlrev_b32_e32 v82, 16, v81
	v_and_b32_e32 v83, 0xffff0000, v81
	v_pk_mul_f32 v[8:9], v[8:9], v[86:87] op_sel_hi:[1,0]
	s_addc_u32 s27, s25, s15
	v_pk_fma_f32 v[8:9], v[88:89], v[82:83], v[8:9] op_sel_hi:[0,1,1]
	v_readlane_b32 s100, v200, 7
	s_add_u32 s26, s34, s14
	s_addc_u32 s27, s36, s15
	v_readlane_b32 s101, v201, 7
	s_nop 1
	v_mov_b32_e32 v82, s100
	v_mov_b32_e32 v81, s101
	s_and_b32 s13, s16, 0x67
	v_pk_mul_f32 v[6:7], v[6:7], v[86:87] op_sel_hi:[1,0]
	s_mul_i32 s90, s13, 0x9000
	v_pk_fma_f32 v[6:7], v[88:89], v[90:91], v[6:7] op_sel_hi:[0,1,1]
	v_lshl_add_u64 v[86:87], v[0:1], 0, s[90:91]
	v_cvt_pk_bf16_f32 v83, v4, v5
	global_store_dword v[86:87], v83, off
	v_cvt_pk_bf16_f32 v83, v6, v7
	global_store_dword v[86:87], v83, off offset:1536
	v_cvt_pk_bf16_f32 v83, v8, v9
	global_store_dword v[86:87], v83, off offset:3072
	s_and_saveexec_b64 s[16:17], s[8:9]
	s_cbranch_execz .LBB0_383
	s_add_u32 s14, s37, s14
	s_addc_u32 s15, s40, s15
	global_store_dword v181, v84, s[14:15]
.LBB0_383:
	s_or_b64 exec, exec, s[16:17]
	s_nop 0
	v_add_f32_e32 v83, v84, v81
	v_max_f32_e32 v81, v82, v82
	v_max_f32_e32 v81, v83, v81
	v_sub_f32_e32 v83, v83, v81
	v_mul_f32_e32 v83, 0x3fb8aa3b, v83
	v_sub_f32_e32 v82, v82, v81
	v_exp_f32_e32 v84, v83
	v_mul_f32_e32 v82, 0x3fb8aa3b, v82
	s_or_b32 s16, s12, 8
	v_exp_f32_e32 v82, v82
	s_ashr_i32 s17, s16, 31
	s_lshl_b64 s[14:15], s[16:17], 2
	s_add_u32 s26, s67, s14
	v_lshlrev_b32_e32 v86, 16, v80
	v_pk_mul_f32 v[4:5], v[4:5], v[84:85] op_sel_hi:[1,0]
	v_and_b32_e32 v87, 0xffff0000, v80
	s_addc_u32 s27, s25, s15
	v_pk_fma_f32 v[4:5], v[82:83], v[86:87], v[4:5] op_sel_hi:[0,1,1]
	v_lshlrev_b32_e32 v86, 16, v79
	v_and_b32_e32 v87, 0xffff0000, v79
	v_readlane_b32 s100, v200, 8
	s_add_u32 s26, s34, s14
	v_pk_mul_f32 v[6:7], v[6:7], v[84:85] op_sel_hi:[1,0]
	s_addc_u32 s27, s36, s15
	v_pk_fma_f32 v[6:7], v[82:83], v[86:87], v[6:7] op_sel_hi:[0,1,1]
	v_lshlrev_b32_e32 v86, 16, v78
	v_and_b32_e32 v87, 0xffff0000, v78
	v_readlane_b32 s101, v201, 8
	s_nop 1
	v_mov_b32_e32 v79, s100
	v_mov_b32_e32 v78, s101
	s_and_b32 s13, s16, 0x68
	v_pk_mul_f32 v[8:9], v[8:9], v[84:85] op_sel_hi:[1,0]
	s_mul_i32 s90, s13, 0x9000
	v_pk_fma_f32 v[8:9], v[82:83], v[86:87], v[8:9] op_sel_hi:[0,1,1]
	v_lshl_add_u64 v[82:83], v[0:1], 0, s[90:91]
	v_cvt_pk_bf16_f32 v80, v4, v5
	global_store_dword v[82:83], v80, off
	v_cvt_pk_bf16_f32 v80, v6, v7
	global_store_dword v[82:83], v80, off offset:1536
	v_cvt_pk_bf16_f32 v80, v8, v9
	global_store_dword v[82:83], v80, off offset:3072
	s_and_saveexec_b64 s[16:17], s[8:9]
	s_cbranch_execz .LBB0_385
	s_add_u32 s14, s37, s14
	s_addc_u32 s15, s40, s15
	global_store_dword v181, v81, s[14:15]
.LBB0_385:
	s_or_b64 exec, exec, s[16:17]
	s_nop 0
	v_add_f32_e32 v80, v81, v78
	v_max_f32_e32 v78, v79, v79
	v_max_f32_e32 v78, v80, v78
	v_sub_f32_e32 v80, v80, v78
	v_mul_f32_e32 v80, 0x3fb8aa3b, v80
	v_sub_f32_e32 v79, v79, v78
	v_exp_f32_e32 v80, v80
	v_mul_f32_e32 v79, 0x3fb8aa3b, v79
	v_exp_f32_e32 v82, v79
	s_or_b32 s16, s12, 9
	s_ashr_i32 s17, s16, 31
	s_lshl_b64 s[14:15], s[16:17], 2
	v_lshlrev_b32_e32 v84, 16, v77
	v_and_b32_e32 v85, 0xffff0000, v77
	v_pk_mul_f32 v[4:5], v[4:5], v[80:81] op_sel_hi:[1,0]
	s_add_u32 s26, s67, s14
	v_pk_fma_f32 v[4:5], v[82:83], v[84:85], v[4:5] op_sel_hi:[0,1,1]
	v_lshlrev_b32_e32 v84, 16, v76
	v_and_b32_e32 v85, 0xffff0000, v76
	v_lshlrev_b32_e32 v76, 16, v75
	v_and_b32_e32 v77, 0xffff0000, v75
	v_pk_mul_f32 v[8:9], v[8:9], v[80:81] op_sel_hi:[1,0]
	s_addc_u32 s27, s25, s15
	v_pk_fma_f32 v[8:9], v[82:83], v[76:77], v[8:9] op_sel_hi:[0,1,1]
	v_readlane_b32 s100, v200, 9
	s_add_u32 s26, s34, s14
	s_addc_u32 s27, s36, s15
	v_readlane_b32 s101, v201, 9
	s_nop 1
	v_mov_b32_e32 v76, s100
	v_mov_b32_e32 v75, s101
	s_and_b32 s13, s16, 0x69
	v_pk_mul_f32 v[6:7], v[6:7], v[80:81] op_sel_hi:[1,0]
	s_mul_i32 s90, s13, 0x9000
	v_pk_fma_f32 v[6:7], v[82:83], v[84:85], v[6:7] op_sel_hi:[0,1,1]
	v_lshl_add_u64 v[80:81], v[0:1], 0, s[90:91]
	v_cvt_pk_bf16_f32 v77, v4, v5
	global_store_dword v[80:81], v77, off
	v_cvt_pk_bf16_f32 v77, v6, v7
	global_store_dword v[80:81], v77, off offset:1536
	v_cvt_pk_bf16_f32 v77, v8, v9
	global_store_dword v[80:81], v77, off offset:3072
	s_and_saveexec_b64 s[16:17], s[8:9]
	s_cbranch_execz .LBB0_387
	s_add_u32 s14, s37, s14
	s_addc_u32 s15, s40, s15
	global_store_dword v181, v78, s[14:15]
.LBB0_387:
	s_or_b64 exec, exec, s[16:17]
	s_nop 0
	v_add_f32_e32 v77, v78, v75
	v_max_f32_e32 v75, v76, v76
	v_max_f32_e32 v75, v77, v75
	v_sub_f32_e32 v77, v77, v75
	v_mul_f32_e32 v77, 0x3fb8aa3b, v77
	v_sub_f32_e32 v76, v76, v75
	v_exp_f32_e32 v78, v77
	v_mul_f32_e32 v76, 0x3fb8aa3b, v76
	s_or_b32 s16, s12, 10
	v_exp_f32_e32 v76, v76
	s_ashr_i32 s17, s16, 31
	s_lshl_b64 s[14:15], s[16:17], 2
	s_add_u32 s26, s67, s14
	v_lshlrev_b32_e32 v80, 16, v74
	v_and_b32_e32 v81, 0xffff0000, v74
	v_pk_mul_f32 v[4:5], v[4:5], v[78:79] op_sel_hi:[1,0]
	s_addc_u32 s27, s25, s15
	v_pk_fma_f32 v[4:5], v[76:77], v[80:81], v[4:5] op_sel_hi:[0,1,1]
	v_lshlrev_b32_e32 v80, 16, v73
	v_and_b32_e32 v81, 0xffff0000, v73
	v_readlane_b32 s100, v200, 10
	s_add_u32 s26, s34, s14
	v_pk_mul_f32 v[6:7], v[6:7], v[78:79] op_sel_hi:[1,0]
	s_addc_u32 s27, s36, s15
	v_pk_fma_f32 v[6:7], v[76:77], v[80:81], v[6:7] op_sel_hi:[0,1,1]
	v_lshlrev_b32_e32 v80, 16, v72
	v_and_b32_e32 v81, 0xffff0000, v72
	v_readlane_b32 s101, v201, 10
	s_nop 1
	v_mov_b32_e32 v73, s100
	v_mov_b32_e32 v72, s101
	s_and_b32 s13, s16, 0x6a
	v_pk_mul_f32 v[8:9], v[8:9], v[78:79] op_sel_hi:[1,0]
	s_mul_i32 s90, s13, 0x9000
	v_pk_fma_f32 v[8:9], v[76:77], v[80:81], v[8:9] op_sel_hi:[0,1,1]
	v_lshl_add_u64 v[76:77], v[0:1], 0, s[90:91]
	v_cvt_pk_bf16_f32 v74, v4, v5
	global_store_dword v[76:77], v74, off
	v_cvt_pk_bf16_f32 v74, v6, v7
	global_store_dword v[76:77], v74, off offset:1536
	v_cvt_pk_bf16_f32 v74, v8, v9
	global_store_dword v[76:77], v74, off offset:3072
	s_and_saveexec_b64 s[16:17], s[8:9]
	s_cbranch_execz .LBB0_389
	s_add_u32 s14, s37, s14
	s_addc_u32 s15, s40, s15
	global_store_dword v181, v75, s[14:15]
.LBB0_389:
	s_or_b64 exec, exec, s[16:17]
	s_nop 0
	v_add_f32_e32 v74, v75, v72
	v_max_f32_e32 v72, v73, v73
	v_max_f32_e32 v72, v74, v72
	v_sub_f32_e32 v74, v74, v72
	v_mul_f32_e32 v74, 0x3fb8aa3b, v74
	v_sub_f32_e32 v73, v73, v72
	v_exp_f32_e32 v74, v74
	v_mul_f32_e32 v73, 0x3fb8aa3b, v73
	v_exp_f32_e32 v76, v73
	s_or_b32 s16, s12, 11
	s_ashr_i32 s17, s16, 31
	s_lshl_b64 s[14:15], s[16:17], 2
	v_lshlrev_b32_e32 v78, 16, v71
	v_and_b32_e32 v79, 0xffff0000, v71
	v_pk_mul_f32 v[4:5], v[4:5], v[74:75] op_sel_hi:[1,0]
	s_add_u32 s26, s67, s14
	v_pk_fma_f32 v[4:5], v[76:77], v[78:79], v[4:5] op_sel_hi:[0,1,1]
	v_lshlrev_b32_e32 v78, 16, v70
	v_and_b32_e32 v79, 0xffff0000, v70
	v_lshlrev_b32_e32 v70, 16, v69
	v_and_b32_e32 v71, 0xffff0000, v69
	v_pk_mul_f32 v[8:9], v[8:9], v[74:75] op_sel_hi:[1,0]
	s_addc_u32 s27, s25, s15
	v_pk_fma_f32 v[8:9], v[76:77], v[70:71], v[8:9] op_sel_hi:[0,1,1]
	v_readlane_b32 s100, v200, 11
	s_add_u32 s26, s34, s14
	s_addc_u32 s27, s36, s15
	v_readlane_b32 s101, v201, 11
	s_nop 1
	v_mov_b32_e32 v70, s100
	v_mov_b32_e32 v69, s101
	s_and_b32 s13, s16, 0x6b
	v_pk_mul_f32 v[6:7], v[6:7], v[74:75] op_sel_hi:[1,0]
	s_mul_i32 s90, s13, 0x9000
	v_pk_fma_f32 v[6:7], v[76:77], v[78:79], v[6:7] op_sel_hi:[0,1,1]
	v_lshl_add_u64 v[74:75], v[0:1], 0, s[90:91]
	v_cvt_pk_bf16_f32 v71, v4, v5
	global_store_dword v[74:75], v71, off
	v_cvt_pk_bf16_f32 v71, v6, v7
	global_store_dword v[74:75], v71, off offset:1536
	v_cvt_pk_bf16_f32 v71, v8, v9
	global_store_dword v[74:75], v71, off offset:3072
	s_and_saveexec_b64 s[16:17], s[8:9]
	s_cbranch_execz .LBB0_391
	s_add_u32 s14, s37, s14
	s_addc_u32 s15, s40, s15
	global_store_dword v181, v72, s[14:15]
.LBB0_391:
	s_or_b64 exec, exec, s[16:17]
	s_nop 0
	v_add_f32_e32 v71, v72, v69
	v_max_f32_e32 v69, v70, v70
	v_max_f32_e32 v69, v71, v69
	v_sub_f32_e32 v71, v71, v69
	v_mul_f32_e32 v71, 0x3fb8aa3b, v71
	v_sub_f32_e32 v70, v70, v69
	v_exp_f32_e32 v72, v71
	v_mul_f32_e32 v70, 0x3fb8aa3b, v70
	s_or_b32 s16, s12, 12
	v_exp_f32_e32 v70, v70
	s_ashr_i32 s17, s16, 31
	s_lshl_b64 s[14:15], s[16:17], 2
	s_add_u32 s26, s67, s14
	v_lshlrev_b32_e32 v74, 16, v68
	v_and_b32_e32 v75, 0xffff0000, v68
	v_pk_mul_f32 v[4:5], v[4:5], v[72:73] op_sel_hi:[1,0]
	s_addc_u32 s27, s25, s15
	v_pk_fma_f32 v[4:5], v[70:71], v[74:75], v[4:5] op_sel_hi:[0,1,1]
	v_lshlrev_b32_e32 v74, 16, v67
	v_and_b32_e32 v75, 0xffff0000, v67
	v_readlane_b32 s100, v200, 12
	s_add_u32 s26, s34, s14
	v_pk_mul_f32 v[6:7], v[6:7], v[72:73] op_sel_hi:[1,0]
	s_addc_u32 s27, s36, s15
	v_pk_fma_f32 v[6:7], v[70:71], v[74:75], v[6:7] op_sel_hi:[0,1,1]
	v_lshlrev_b32_e32 v74, 16, v66
	v_and_b32_e32 v75, 0xffff0000, v66
	v_readlane_b32 s101, v201, 12
	s_nop 1
	v_mov_b32_e32 v67, s100
	v_mov_b32_e32 v66, s101
	s_and_b32 s13, s16, 0x6c
	v_pk_mul_f32 v[8:9], v[8:9], v[72:73] op_sel_hi:[1,0]
	s_mul_i32 s90, s13, 0x9000
	v_pk_fma_f32 v[8:9], v[70:71], v[74:75], v[8:9] op_sel_hi:[0,1,1]
	v_lshl_add_u64 v[70:71], v[0:1], 0, s[90:91]
	v_cvt_pk_bf16_f32 v68, v4, v5
	global_store_dword v[70:71], v68, off
	v_cvt_pk_bf16_f32 v68, v6, v7
	global_store_dword v[70:71], v68, off offset:1536
	v_cvt_pk_bf16_f32 v68, v8, v9
	global_store_dword v[70:71], v68, off offset:3072
	s_and_saveexec_b64 s[16:17], s[8:9]
	s_cbranch_execz .LBB0_393
	s_add_u32 s14, s37, s14
	s_addc_u32 s15, s40, s15
	global_store_dword v181, v69, s[14:15]
.LBB0_393:
	s_or_b64 exec, exec, s[16:17]
	s_nop 0
	v_add_f32_e32 v68, v69, v66
	v_max_f32_e32 v66, v67, v67
	v_max_f32_e32 v66, v68, v66
	v_sub_f32_e32 v68, v68, v66
	v_mul_f32_e32 v68, 0x3fb8aa3b, v68
	v_sub_f32_e32 v67, v67, v66
	v_exp_f32_e32 v68, v68
	v_mul_f32_e32 v67, 0x3fb8aa3b, v67
	v_exp_f32_e32 v70, v67
	s_or_b32 s16, s12, 13
	s_ashr_i32 s17, s16, 31
	s_lshl_b64 s[14:15], s[16:17], 2
	v_lshlrev_b32_e32 v72, 16, v65
	v_and_b32_e32 v73, 0xffff0000, v65
	v_pk_mul_f32 v[4:5], v[4:5], v[68:69] op_sel_hi:[1,0]
	s_add_u32 s26, s67, s14
	v_pk_fma_f32 v[4:5], v[70:71], v[72:73], v[4:5] op_sel_hi:[0,1,1]
	v_lshlrev_b32_e32 v72, 16, v64
	v_and_b32_e32 v73, 0xffff0000, v64
	v_lshlrev_b32_e32 v64, 16, v63
	v_and_b32_e32 v65, 0xffff0000, v63
	v_pk_mul_f32 v[8:9], v[8:9], v[68:69] op_sel_hi:[1,0]
	s_addc_u32 s27, s25, s15
	v_pk_fma_f32 v[8:9], v[70:71], v[64:65], v[8:9] op_sel_hi:[0,1,1]
	v_readlane_b32 s100, v200, 13
	s_add_u32 s26, s34, s14
	s_addc_u32 s27, s36, s15
	v_readlane_b32 s101, v201, 13
	s_nop 1
	v_mov_b32_e32 v64, s100
	v_mov_b32_e32 v63, s101
	s_and_b32 s13, s16, 0x6d
	v_pk_mul_f32 v[6:7], v[6:7], v[68:69] op_sel_hi:[1,0]
	s_mul_i32 s90, s13, 0x9000
	v_pk_fma_f32 v[6:7], v[70:71], v[72:73], v[6:7] op_sel_hi:[0,1,1]
	v_lshl_add_u64 v[68:69], v[0:1], 0, s[90:91]
	v_cvt_pk_bf16_f32 v65, v4, v5
	global_store_dword v[68:69], v65, off
	v_cvt_pk_bf16_f32 v65, v6, v7
	global_store_dword v[68:69], v65, off offset:1536
	v_cvt_pk_bf16_f32 v65, v8, v9
	global_store_dword v[68:69], v65, off offset:3072
	s_and_saveexec_b64 s[16:17], s[8:9]
	s_cbranch_execz .LBB0_395
	s_add_u32 s14, s37, s14
	s_addc_u32 s15, s40, s15
	global_store_dword v181, v66, s[14:15]
.LBB0_395:
	s_or_b64 exec, exec, s[16:17]
	s_nop 0
	v_add_f32_e32 v65, v66, v63
	v_max_f32_e32 v63, v64, v64
	v_max_f32_e32 v63, v65, v63
	v_sub_f32_e32 v65, v65, v63
	v_mul_f32_e32 v65, 0x3fb8aa3b, v65
	v_sub_f32_e32 v64, v64, v63
	v_exp_f32_e32 v66, v65
	v_mul_f32_e32 v64, 0x3fb8aa3b, v64
	s_or_b32 s16, s12, 14
	v_exp_f32_e32 v64, v64
	s_ashr_i32 s17, s16, 31
	s_lshl_b64 s[14:15], s[16:17], 2
	s_add_u32 s26, s67, s14
	v_lshlrev_b32_e32 v68, 16, v62
	v_pk_mul_f32 v[4:5], v[4:5], v[66:67] op_sel_hi:[1,0]
	v_and_b32_e32 v69, 0xffff0000, v62
	s_addc_u32 s27, s25, s15
	v_pk_fma_f32 v[4:5], v[64:65], v[68:69], v[4:5] op_sel_hi:[0,1,1]
	v_lshlrev_b32_e32 v68, 16, v61
	v_and_b32_e32 v69, 0xffff0000, v61
	v_readlane_b32 s100, v200, 14
	s_add_u32 s26, s34, s14
	v_pk_mul_f32 v[6:7], v[6:7], v[66:67] op_sel_hi:[1,0]
	s_addc_u32 s27, s36, s15
	v_pk_fma_f32 v[6:7], v[64:65], v[68:69], v[6:7] op_sel_hi:[0,1,1]
	v_lshlrev_b32_e32 v68, 16, v60
	v_and_b32_e32 v69, 0xffff0000, v60
	v_readlane_b32 s101, v201, 14
	s_nop 1
	v_mov_b32_e32 v61, s100
	v_mov_b32_e32 v60, s101
	s_and_b32 s13, s16, 0x6e
	v_pk_mul_f32 v[8:9], v[8:9], v[66:67] op_sel_hi:[1,0]
	s_mul_i32 s90, s13, 0x9000
	v_pk_fma_f32 v[8:9], v[64:65], v[68:69], v[8:9] op_sel_hi:[0,1,1]
	v_lshl_add_u64 v[64:65], v[0:1], 0, s[90:91]
	v_cvt_pk_bf16_f32 v62, v4, v5
	global_store_dword v[64:65], v62, off
	v_cvt_pk_bf16_f32 v62, v6, v7
	global_store_dword v[64:65], v62, off offset:1536
	v_cvt_pk_bf16_f32 v62, v8, v9
	global_store_dword v[64:65], v62, off offset:3072
	s_and_saveexec_b64 s[16:17], s[8:9]
	s_cbranch_execz .LBB0_397
	s_add_u32 s14, s37, s14
	s_addc_u32 s15, s40, s15
	global_store_dword v181, v63, s[14:15]
.LBB0_397:
	s_or_b64 exec, exec, s[16:17]
	s_nop 0
	v_add_f32_e32 v62, v63, v60
	v_max_f32_e32 v60, v61, v61
	v_max_f32_e32 v60, v62, v60
	v_sub_f32_e32 v62, v62, v60
	v_mul_f32_e32 v62, 0x3fb8aa3b, v62
	v_sub_f32_e32 v61, v61, v60
	v_exp_f32_e32 v62, v62
	v_mul_f32_e32 v61, 0x3fb8aa3b, v61
	v_exp_f32_e32 v64, v61
	s_or_b32 s16, s12, 15
	s_ashr_i32 s17, s16, 31
	s_lshl_b64 s[14:15], s[16:17], 2
	v_lshlrev_b32_e32 v66, 16, v59
	v_and_b32_e32 v67, 0xffff0000, v59
	v_pk_mul_f32 v[4:5], v[4:5], v[62:63] op_sel_hi:[1,0]
	s_add_u32 s26, s67, s14
	v_pk_fma_f32 v[4:5], v[64:65], v[66:67], v[4:5] op_sel_hi:[0,1,1]
	v_lshlrev_b32_e32 v66, 16, v58
	v_and_b32_e32 v67, 0xffff0000, v58
	v_lshlrev_b32_e32 v58, 16, v57
	v_and_b32_e32 v59, 0xffff0000, v57
	v_pk_mul_f32 v[8:9], v[8:9], v[62:63] op_sel_hi:[1,0]
	s_addc_u32 s27, s25, s15
	v_pk_fma_f32 v[8:9], v[64:65], v[58:59], v[8:9] op_sel_hi:[0,1,1]
	v_readlane_b32 s100, v200, 15
	s_add_u32 s26, s34, s14
	s_addc_u32 s27, s36, s15
	v_readlane_b32 s101, v201, 15
	s_nop 1
	v_mov_b32_e32 v58, s100
	v_mov_b32_e32 v57, s101
	s_and_b32 s13, s16, 0x6f
	v_pk_mul_f32 v[6:7], v[6:7], v[62:63] op_sel_hi:[1,0]
	s_mul_i32 s90, s13, 0x9000
	v_pk_fma_f32 v[6:7], v[64:65], v[66:67], v[6:7] op_sel_hi:[0,1,1]
	v_lshl_add_u64 v[62:63], v[0:1], 0, s[90:91]
	v_cvt_pk_bf16_f32 v59, v4, v5
	global_store_dword v[62:63], v59, off
	v_cvt_pk_bf16_f32 v59, v6, v7
	global_store_dword v[62:63], v59, off offset:1536
	v_cvt_pk_bf16_f32 v59, v8, v9
	global_store_dword v[62:63], v59, off offset:3072
	s_and_saveexec_b64 s[16:17], s[8:9]
	s_cbranch_execz .LBB0_399
	s_add_u32 s14, s37, s14
	s_addc_u32 s15, s40, s15
	global_store_dword v181, v60, s[14:15]
.LBB0_399:
	s_or_b64 exec, exec, s[16:17]
	s_nop 0
	v_add_f32_e32 v59, v60, v57
	v_max_f32_e32 v57, v58, v58
	v_max_f32_e32 v57, v59, v57
	v_sub_f32_e32 v59, v59, v57
	v_mul_f32_e32 v59, 0x3fb8aa3b, v59
	v_sub_f32_e32 v58, v58, v57
	v_exp_f32_e32 v60, v59
	v_mul_f32_e32 v58, 0x3fb8aa3b, v58
	s_or_b32 s16, s12, 16
	v_exp_f32_e32 v58, v58
	s_ashr_i32 s17, s16, 31
	s_lshl_b64 s[14:15], s[16:17], 2
	s_add_u32 s26, s67, s14
	v_lshlrev_b32_e32 v62, 16, v56
	v_and_b32_e32 v63, 0xffff0000, v56
	v_pk_mul_f32 v[4:5], v[4:5], v[60:61] op_sel_hi:[1,0]
	s_addc_u32 s27, s25, s15
	v_pk_fma_f32 v[4:5], v[58:59], v[62:63], v[4:5] op_sel_hi:[0,1,1]
	v_lshlrev_b32_e32 v62, 16, v55
	v_and_b32_e32 v63, 0xffff0000, v55
	v_readlane_b32 s100, v200, 16
	s_add_u32 s26, s34, s14
	v_pk_mul_f32 v[6:7], v[6:7], v[60:61] op_sel_hi:[1,0]
	s_addc_u32 s27, s36, s15
	v_pk_fma_f32 v[6:7], v[58:59], v[62:63], v[6:7] op_sel_hi:[0,1,1]
	v_lshlrev_b32_e32 v62, 16, v54
	v_and_b32_e32 v63, 0xffff0000, v54
	v_readlane_b32 s101, v201, 16
	s_nop 1
	v_mov_b32_e32 v55, s100
	v_mov_b32_e32 v54, s101
	s_and_b32 s13, s16, 0x70
	v_pk_mul_f32 v[8:9], v[8:9], v[60:61] op_sel_hi:[1,0]
	s_mul_i32 s90, s13, 0x9000
	v_pk_fma_f32 v[8:9], v[58:59], v[62:63], v[8:9] op_sel_hi:[0,1,1]
	v_lshl_add_u64 v[58:59], v[0:1], 0, s[90:91]
	v_cvt_pk_bf16_f32 v56, v4, v5
	global_store_dword v[58:59], v56, off
	v_cvt_pk_bf16_f32 v56, v6, v7
	global_store_dword v[58:59], v56, off offset:1536
	v_cvt_pk_bf16_f32 v56, v8, v9
	global_store_dword v[58:59], v56, off offset:3072
	s_and_saveexec_b64 s[16:17], s[8:9]
	s_cbranch_execz .LBB0_401
	s_add_u32 s14, s37, s14
	s_addc_u32 s15, s40, s15
	global_store_dword v181, v57, s[14:15]
.LBB0_401:
	s_or_b64 exec, exec, s[16:17]
	s_nop 0
	v_add_f32_e32 v56, v57, v54
	v_max_f32_e32 v54, v55, v55
	v_max_f32_e32 v54, v56, v54
	v_sub_f32_e32 v56, v56, v54
	v_mul_f32_e32 v56, 0x3fb8aa3b, v56
	v_sub_f32_e32 v55, v55, v54
	v_exp_f32_e32 v56, v56
	v_mul_f32_e32 v55, 0x3fb8aa3b, v55
	v_exp_f32_e32 v58, v55
	s_or_b32 s16, s12, 17
	s_ashr_i32 s17, s16, 31
	s_lshl_b64 s[14:15], s[16:17], 2
	v_lshlrev_b32_e32 v60, 16, v53
	v_and_b32_e32 v61, 0xffff0000, v53
	v_pk_mul_f32 v[4:5], v[4:5], v[56:57] op_sel_hi:[1,0]
	s_add_u32 s26, s67, s14
	v_pk_fma_f32 v[4:5], v[58:59], v[60:61], v[4:5] op_sel_hi:[0,1,1]
	v_lshlrev_b32_e32 v60, 16, v52
	v_and_b32_e32 v61, 0xffff0000, v52
	v_lshlrev_b32_e32 v52, 16, v51
	v_and_b32_e32 v53, 0xffff0000, v51
	v_pk_mul_f32 v[8:9], v[8:9], v[56:57] op_sel_hi:[1,0]
	s_addc_u32 s27, s25, s15
	v_pk_fma_f32 v[8:9], v[58:59], v[52:53], v[8:9] op_sel_hi:[0,1,1]
	v_readlane_b32 s100, v200, 17
	s_add_u32 s26, s34, s14
	s_addc_u32 s27, s36, s15
	v_readlane_b32 s101, v201, 17
	s_nop 1
	v_mov_b32_e32 v52, s100
	v_mov_b32_e32 v51, s101
	s_and_b32 s13, s16, 0x71
	v_pk_mul_f32 v[6:7], v[6:7], v[56:57] op_sel_hi:[1,0]
	s_mul_i32 s90, s13, 0x9000
	v_pk_fma_f32 v[6:7], v[58:59], v[60:61], v[6:7] op_sel_hi:[0,1,1]
	v_lshl_add_u64 v[56:57], v[0:1], 0, s[90:91]
	v_cvt_pk_bf16_f32 v53, v4, v5
	global_store_dword v[56:57], v53, off
	v_cvt_pk_bf16_f32 v53, v6, v7
	global_store_dword v[56:57], v53, off offset:1536
	v_cvt_pk_bf16_f32 v53, v8, v9
	global_store_dword v[56:57], v53, off offset:3072
	s_and_saveexec_b64 s[16:17], s[8:9]
	s_cbranch_execz .LBB0_403
	s_add_u32 s14, s37, s14
	s_addc_u32 s15, s40, s15
	global_store_dword v181, v54, s[14:15]
.LBB0_403:
	s_or_b64 exec, exec, s[16:17]
	s_nop 0
	v_add_f32_e32 v53, v54, v51
	v_max_f32_e32 v51, v52, v52
	v_max_f32_e32 v51, v53, v51
	v_sub_f32_e32 v53, v53, v51
	v_mul_f32_e32 v53, 0x3fb8aa3b, v53
	v_sub_f32_e32 v52, v52, v51
	v_exp_f32_e32 v54, v53
	v_mul_f32_e32 v52, 0x3fb8aa3b, v52
	s_or_b32 s16, s12, 18
	v_exp_f32_e32 v52, v52
	s_ashr_i32 s17, s16, 31
	s_lshl_b64 s[14:15], s[16:17], 2
	s_add_u32 s26, s67, s14
	v_lshlrev_b32_e32 v56, 16, v50
	v_and_b32_e32 v57, 0xffff0000, v50
	v_pk_mul_f32 v[4:5], v[4:5], v[54:55] op_sel_hi:[1,0]
	s_addc_u32 s27, s25, s15
	v_pk_fma_f32 v[4:5], v[52:53], v[56:57], v[4:5] op_sel_hi:[0,1,1]
	v_lshlrev_b32_e32 v56, 16, v49
	v_and_b32_e32 v57, 0xffff0000, v49
	v_readlane_b32 s100, v200, 18
	s_add_u32 s26, s34, s14
	v_pk_mul_f32 v[6:7], v[6:7], v[54:55] op_sel_hi:[1,0]
	s_addc_u32 s27, s36, s15
	v_pk_fma_f32 v[6:7], v[52:53], v[56:57], v[6:7] op_sel_hi:[0,1,1]
	v_lshlrev_b32_e32 v56, 16, v48
	v_and_b32_e32 v57, 0xffff0000, v48
	v_readlane_b32 s101, v201, 18
	s_nop 1
	v_mov_b32_e32 v49, s100
	v_mov_b32_e32 v48, s101
	s_and_b32 s13, s16, 0x72
	v_pk_mul_f32 v[8:9], v[8:9], v[54:55] op_sel_hi:[1,0]
	s_mul_i32 s90, s13, 0x9000
	v_pk_fma_f32 v[8:9], v[52:53], v[56:57], v[8:9] op_sel_hi:[0,1,1]
	v_lshl_add_u64 v[52:53], v[0:1], 0, s[90:91]
	v_cvt_pk_bf16_f32 v50, v4, v5
	global_store_dword v[52:53], v50, off
	v_cvt_pk_bf16_f32 v50, v6, v7
	global_store_dword v[52:53], v50, off offset:1536
	v_cvt_pk_bf16_f32 v50, v8, v9
	global_store_dword v[52:53], v50, off offset:3072
	s_and_saveexec_b64 s[16:17], s[8:9]
	s_cbranch_execz .LBB0_405
	s_add_u32 s14, s37, s14
	s_addc_u32 s15, s40, s15
	global_store_dword v181, v51, s[14:15]
.LBB0_405:
	s_or_b64 exec, exec, s[16:17]
	s_nop 0
	v_add_f32_e32 v50, v51, v48
	v_max_f32_e32 v48, v49, v49
	v_max_f32_e32 v48, v50, v48
	v_sub_f32_e32 v50, v50, v48
	v_mul_f32_e32 v50, 0x3fb8aa3b, v50
	v_sub_f32_e32 v49, v49, v48
	v_exp_f32_e32 v50, v50
	v_mul_f32_e32 v49, 0x3fb8aa3b, v49
	v_exp_f32_e32 v52, v49
	s_or_b32 s16, s12, 19
	s_ashr_i32 s17, s16, 31
	s_lshl_b64 s[14:15], s[16:17], 2
	v_lshlrev_b32_e32 v54, 16, v47
	v_and_b32_e32 v55, 0xffff0000, v47
	v_pk_mul_f32 v[4:5], v[4:5], v[50:51] op_sel_hi:[1,0]
	s_add_u32 s26, s67, s14
	v_pk_fma_f32 v[4:5], v[52:53], v[54:55], v[4:5] op_sel_hi:[0,1,1]
	v_lshlrev_b32_e32 v54, 16, v46
	v_and_b32_e32 v55, 0xffff0000, v46
	v_lshlrev_b32_e32 v46, 16, v45
	v_and_b32_e32 v47, 0xffff0000, v45
	v_pk_mul_f32 v[8:9], v[8:9], v[50:51] op_sel_hi:[1,0]
	s_addc_u32 s27, s25, s15
	v_pk_fma_f32 v[8:9], v[52:53], v[46:47], v[8:9] op_sel_hi:[0,1,1]
	v_readlane_b32 s100, v200, 19
	s_add_u32 s26, s34, s14
	s_addc_u32 s27, s36, s15
	v_readlane_b32 s101, v201, 19
	s_nop 1
	v_mov_b32_e32 v46, s100
	v_mov_b32_e32 v45, s101
	s_and_b32 s13, s16, 0x73
	v_pk_mul_f32 v[6:7], v[6:7], v[50:51] op_sel_hi:[1,0]
	s_mul_i32 s90, s13, 0x9000
	v_pk_fma_f32 v[6:7], v[52:53], v[54:55], v[6:7] op_sel_hi:[0,1,1]
	v_lshl_add_u64 v[50:51], v[0:1], 0, s[90:91]
	v_cvt_pk_bf16_f32 v47, v4, v5
	global_store_dword v[50:51], v47, off
	v_cvt_pk_bf16_f32 v47, v6, v7
	global_store_dword v[50:51], v47, off offset:1536
	v_cvt_pk_bf16_f32 v47, v8, v9
	global_store_dword v[50:51], v47, off offset:3072
	s_and_saveexec_b64 s[16:17], s[8:9]
	s_cbranch_execz .LBB0_407
	s_add_u32 s14, s37, s14
	s_addc_u32 s15, s40, s15
	global_store_dword v181, v48, s[14:15]
.LBB0_407:
	s_or_b64 exec, exec, s[16:17]
	s_nop 0
	v_add_f32_e32 v47, v48, v45
	v_max_f32_e32 v45, v46, v46
	v_max_f32_e32 v45, v47, v45
	v_sub_f32_e32 v47, v47, v45
	v_mul_f32_e32 v47, 0x3fb8aa3b, v47
	v_sub_f32_e32 v46, v46, v45
	v_exp_f32_e32 v48, v47
	v_mul_f32_e32 v46, 0x3fb8aa3b, v46
	s_or_b32 s16, s12, 20
	v_exp_f32_e32 v46, v46
	s_ashr_i32 s17, s16, 31
	s_lshl_b64 s[14:15], s[16:17], 2
	s_add_u32 s26, s67, s14
	v_lshlrev_b32_e32 v50, 16, v44
	v_pk_mul_f32 v[4:5], v[4:5], v[48:49] op_sel_hi:[1,0]
	v_and_b32_e32 v51, 0xffff0000, v44
	s_addc_u32 s27, s25, s15
	v_pk_fma_f32 v[4:5], v[46:47], v[50:51], v[4:5] op_sel_hi:[0,1,1]
	v_lshlrev_b32_e32 v50, 16, v43
	v_and_b32_e32 v51, 0xffff0000, v43
	v_readlane_b32 s100, v200, 20
	s_add_u32 s26, s34, s14
	v_pk_mul_f32 v[6:7], v[6:7], v[48:49] op_sel_hi:[1,0]
	s_addc_u32 s27, s36, s15
	v_pk_fma_f32 v[6:7], v[46:47], v[50:51], v[6:7] op_sel_hi:[0,1,1]
	v_lshlrev_b32_e32 v50, 16, v42
	v_and_b32_e32 v51, 0xffff0000, v42
	v_readlane_b32 s101, v201, 20
	s_nop 1
	v_mov_b32_e32 v43, s100
	v_mov_b32_e32 v42, s101
	s_and_b32 s13, s16, 0x74
	v_pk_mul_f32 v[8:9], v[8:9], v[48:49] op_sel_hi:[1,0]
	s_mul_i32 s90, s13, 0x9000
	v_pk_fma_f32 v[8:9], v[46:47], v[50:51], v[8:9] op_sel_hi:[0,1,1]
	v_lshl_add_u64 v[46:47], v[0:1], 0, s[90:91]
	v_cvt_pk_bf16_f32 v44, v4, v5
	global_store_dword v[46:47], v44, off
	v_cvt_pk_bf16_f32 v44, v6, v7
	global_store_dword v[46:47], v44, off offset:1536
	v_cvt_pk_bf16_f32 v44, v8, v9
	global_store_dword v[46:47], v44, off offset:3072
	s_and_saveexec_b64 s[16:17], s[8:9]
	s_cbranch_execz .LBB0_409
	s_add_u32 s14, s37, s14
	s_addc_u32 s15, s40, s15
	global_store_dword v181, v45, s[14:15]
.LBB0_409:
	s_or_b64 exec, exec, s[16:17]
	s_nop 0
	v_add_f32_e32 v44, v45, v42
	v_max_f32_e32 v42, v43, v43
	v_max_f32_e32 v42, v44, v42
	v_sub_f32_e32 v44, v44, v42
	v_mul_f32_e32 v44, 0x3fb8aa3b, v44
	v_sub_f32_e32 v43, v43, v42
	v_exp_f32_e32 v44, v44
	v_mul_f32_e32 v43, 0x3fb8aa3b, v43
	v_exp_f32_e32 v46, v43
	s_or_b32 s16, s12, 21
	s_ashr_i32 s17, s16, 31
	s_lshl_b64 s[14:15], s[16:17], 2
	v_lshlrev_b32_e32 v48, 16, v41
	v_and_b32_e32 v49, 0xffff0000, v41
	v_pk_mul_f32 v[4:5], v[4:5], v[44:45] op_sel_hi:[1,0]
	s_add_u32 s26, s67, s14
	v_pk_fma_f32 v[4:5], v[46:47], v[48:49], v[4:5] op_sel_hi:[0,1,1]
	v_lshlrev_b32_e32 v48, 16, v40
	v_and_b32_e32 v49, 0xffff0000, v40
	v_lshlrev_b32_e32 v40, 16, v39
	v_and_b32_e32 v41, 0xffff0000, v39
	v_pk_mul_f32 v[8:9], v[8:9], v[44:45] op_sel_hi:[1,0]
	s_addc_u32 s27, s25, s15
	v_pk_fma_f32 v[8:9], v[46:47], v[40:41], v[8:9] op_sel_hi:[0,1,1]
	v_readlane_b32 s100, v200, 21
	s_add_u32 s26, s34, s14
	s_addc_u32 s27, s36, s15
	v_readlane_b32 s101, v201, 21
	s_nop 1
	v_mov_b32_e32 v40, s100
	v_mov_b32_e32 v39, s101
	s_and_b32 s13, s16, 0x75
	v_pk_mul_f32 v[6:7], v[6:7], v[44:45] op_sel_hi:[1,0]
	s_mul_i32 s90, s13, 0x9000
	v_pk_fma_f32 v[6:7], v[46:47], v[48:49], v[6:7] op_sel_hi:[0,1,1]
	v_lshl_add_u64 v[44:45], v[0:1], 0, s[90:91]
	v_cvt_pk_bf16_f32 v41, v4, v5
	global_store_dword v[44:45], v41, off
	v_cvt_pk_bf16_f32 v41, v6, v7
	global_store_dword v[44:45], v41, off offset:1536
	v_cvt_pk_bf16_f32 v41, v8, v9
	global_store_dword v[44:45], v41, off offset:3072
	s_and_saveexec_b64 s[16:17], s[8:9]
	s_cbranch_execz .LBB0_411
	s_add_u32 s14, s37, s14
	s_addc_u32 s15, s40, s15
	global_store_dword v181, v42, s[14:15]
.LBB0_411:
	s_or_b64 exec, exec, s[16:17]
	s_nop 0
	v_add_f32_e32 v41, v42, v39
	v_max_f32_e32 v39, v40, v40
	v_max_f32_e32 v39, v41, v39
	v_sub_f32_e32 v41, v41, v39
	v_mul_f32_e32 v41, 0x3fb8aa3b, v41
	v_sub_f32_e32 v40, v40, v39
	v_exp_f32_e32 v42, v41
	v_mul_f32_e32 v40, 0x3fb8aa3b, v40
	s_or_b32 s16, s12, 22
	v_exp_f32_e32 v40, v40
	s_ashr_i32 s17, s16, 31
	s_lshl_b64 s[14:15], s[16:17], 2
	s_add_u32 s26, s67, s14
	v_lshlrev_b32_e32 v44, 16, v38
	v_and_b32_e32 v45, 0xffff0000, v38
	v_pk_mul_f32 v[4:5], v[4:5], v[42:43] op_sel_hi:[1,0]
	s_addc_u32 s27, s25, s15
	v_pk_fma_f32 v[4:5], v[40:41], v[44:45], v[4:5] op_sel_hi:[0,1,1]
	v_lshlrev_b32_e32 v44, 16, v37
	v_and_b32_e32 v45, 0xffff0000, v37
	v_readlane_b32 s100, v200, 22
	s_add_u32 s26, s34, s14
	v_pk_mul_f32 v[6:7], v[6:7], v[42:43] op_sel_hi:[1,0]
	s_addc_u32 s27, s36, s15
	v_pk_fma_f32 v[6:7], v[40:41], v[44:45], v[6:7] op_sel_hi:[0,1,1]
	v_lshlrev_b32_e32 v44, 16, v36
	v_and_b32_e32 v45, 0xffff0000, v36
	v_readlane_b32 s101, v201, 22
	s_nop 1
	v_mov_b32_e32 v37, s100
	v_mov_b32_e32 v36, s101
	s_and_b32 s13, s16, 0x76
	v_pk_mul_f32 v[8:9], v[8:9], v[42:43] op_sel_hi:[1,0]
	s_mul_i32 s90, s13, 0x9000
	v_pk_fma_f32 v[8:9], v[40:41], v[44:45], v[8:9] op_sel_hi:[0,1,1]
	v_lshl_add_u64 v[40:41], v[0:1], 0, s[90:91]
	v_cvt_pk_bf16_f32 v38, v4, v5
	global_store_dword v[40:41], v38, off
	v_cvt_pk_bf16_f32 v38, v6, v7
	global_store_dword v[40:41], v38, off offset:1536
	v_cvt_pk_bf16_f32 v38, v8, v9
	global_store_dword v[40:41], v38, off offset:3072
	s_and_saveexec_b64 s[16:17], s[8:9]
	s_cbranch_execz .LBB0_413
	s_add_u32 s14, s37, s14
	s_addc_u32 s15, s40, s15
	global_store_dword v181, v39, s[14:15]
.LBB0_413:
	s_or_b64 exec, exec, s[16:17]
	s_nop 0
	v_add_f32_e32 v38, v39, v36
	v_max_f32_e32 v36, v37, v37
	v_max_f32_e32 v36, v38, v36
	v_sub_f32_e32 v38, v38, v36
	v_mul_f32_e32 v38, 0x3fb8aa3b, v38
	v_sub_f32_e32 v37, v37, v36
	v_exp_f32_e32 v38, v38
	v_mul_f32_e32 v37, 0x3fb8aa3b, v37
	v_exp_f32_e32 v40, v37
	s_or_b32 s16, s12, 23
	s_ashr_i32 s17, s16, 31
	s_lshl_b64 s[14:15], s[16:17], 2
	v_lshlrev_b32_e32 v42, 16, v35
	v_and_b32_e32 v43, 0xffff0000, v35
	v_pk_mul_f32 v[4:5], v[4:5], v[38:39] op_sel_hi:[1,0]
	s_add_u32 s26, s67, s14
	v_pk_fma_f32 v[4:5], v[40:41], v[42:43], v[4:5] op_sel_hi:[0,1,1]
	v_lshlrev_b32_e32 v42, 16, v34
	v_and_b32_e32 v43, 0xffff0000, v34
	v_lshlrev_b32_e32 v34, 16, v33
	v_and_b32_e32 v35, 0xffff0000, v33
	v_pk_mul_f32 v[8:9], v[8:9], v[38:39] op_sel_hi:[1,0]
	s_addc_u32 s27, s25, s15
	v_pk_fma_f32 v[8:9], v[40:41], v[34:35], v[8:9] op_sel_hi:[0,1,1]
	v_readlane_b32 s100, v200, 23
	s_add_u32 s26, s34, s14
	s_addc_u32 s27, s36, s15
	v_readlane_b32 s101, v201, 23
	s_nop 1
	v_mov_b32_e32 v34, s100
	v_mov_b32_e32 v33, s101
	s_and_b32 s13, s16, 0x77
	v_pk_mul_f32 v[6:7], v[6:7], v[38:39] op_sel_hi:[1,0]
	s_mul_i32 s90, s13, 0x9000
	v_pk_fma_f32 v[6:7], v[40:41], v[42:43], v[6:7] op_sel_hi:[0,1,1]
	v_lshl_add_u64 v[38:39], v[0:1], 0, s[90:91]
	v_cvt_pk_bf16_f32 v35, v4, v5
	global_store_dword v[38:39], v35, off
	v_cvt_pk_bf16_f32 v35, v6, v7
	global_store_dword v[38:39], v35, off offset:1536
	v_cvt_pk_bf16_f32 v35, v8, v9
	global_store_dword v[38:39], v35, off offset:3072
	s_and_saveexec_b64 s[16:17], s[8:9]
	s_cbranch_execz .LBB0_415
	s_add_u32 s14, s37, s14
	s_addc_u32 s15, s40, s15
	global_store_dword v181, v36, s[14:15]
.LBB0_415:
	s_or_b64 exec, exec, s[16:17]
	s_nop 0
	v_add_f32_e32 v35, v36, v33
	v_max_f32_e32 v33, v34, v34
	v_max_f32_e32 v33, v35, v33
	v_sub_f32_e32 v35, v35, v33
	v_mul_f32_e32 v35, 0x3fb8aa3b, v35
	v_sub_f32_e32 v34, v34, v33
	v_exp_f32_e32 v36, v35
	v_mul_f32_e32 v34, 0x3fb8aa3b, v34
	s_or_b32 s16, s12, 24
	v_exp_f32_e32 v34, v34
	s_ashr_i32 s17, s16, 31
	s_lshl_b64 s[14:15], s[16:17], 2
	s_add_u32 s26, s67, s14
	v_lshlrev_b32_e32 v38, 16, v32
	v_and_b32_e32 v39, 0xffff0000, v32
	v_pk_mul_f32 v[4:5], v[4:5], v[36:37] op_sel_hi:[1,0]
	s_addc_u32 s27, s25, s15
	v_pk_fma_f32 v[4:5], v[34:35], v[38:39], v[4:5] op_sel_hi:[0,1,1]
	v_lshlrev_b32_e32 v38, 16, v31
	v_and_b32_e32 v39, 0xffff0000, v31
	v_readlane_b32 s100, v200, 24
	s_add_u32 s26, s34, s14
	v_pk_mul_f32 v[6:7], v[6:7], v[36:37] op_sel_hi:[1,0]
	s_addc_u32 s27, s36, s15
	v_pk_fma_f32 v[6:7], v[34:35], v[38:39], v[6:7] op_sel_hi:[0,1,1]
	v_lshlrev_b32_e32 v38, 16, v30
	v_and_b32_e32 v39, 0xffff0000, v30
	v_readlane_b32 s101, v201, 24
	s_nop 1
	v_mov_b32_e32 v31, s100
	v_mov_b32_e32 v30, s101
	s_and_b32 s13, s16, 0x78
	v_pk_mul_f32 v[8:9], v[8:9], v[36:37] op_sel_hi:[1,0]
	s_mul_i32 s90, s13, 0x9000
	v_pk_fma_f32 v[8:9], v[34:35], v[38:39], v[8:9] op_sel_hi:[0,1,1]
	v_lshl_add_u64 v[34:35], v[0:1], 0, s[90:91]
	v_cvt_pk_bf16_f32 v32, v4, v5
	global_store_dword v[34:35], v32, off
	v_cvt_pk_bf16_f32 v32, v6, v7
	global_store_dword v[34:35], v32, off offset:1536
	v_cvt_pk_bf16_f32 v32, v8, v9
	global_store_dword v[34:35], v32, off offset:3072
	s_and_saveexec_b64 s[16:17], s[8:9]
	s_cbranch_execz .LBB0_417
	s_add_u32 s14, s37, s14
	s_addc_u32 s15, s40, s15
	global_store_dword v181, v33, s[14:15]
.LBB0_417:
	s_or_b64 exec, exec, s[16:17]
	s_nop 0
	v_add_f32_e32 v32, v33, v30
	v_max_f32_e32 v30, v31, v31
	v_max_f32_e32 v30, v32, v30
	v_sub_f32_e32 v32, v32, v30
	v_mul_f32_e32 v32, 0x3fb8aa3b, v32
	v_sub_f32_e32 v31, v31, v30
	v_exp_f32_e32 v32, v32
	v_mul_f32_e32 v31, 0x3fb8aa3b, v31
	v_exp_f32_e32 v34, v31
	s_or_b32 s16, s12, 25
	s_ashr_i32 s17, s16, 31
	s_lshl_b64 s[14:15], s[16:17], 2
	v_lshlrev_b32_e32 v36, 16, v29
	v_and_b32_e32 v37, 0xffff0000, v29
	v_pk_mul_f32 v[4:5], v[4:5], v[32:33] op_sel_hi:[1,0]
	s_add_u32 s26, s67, s14
	v_pk_fma_f32 v[4:5], v[34:35], v[36:37], v[4:5] op_sel_hi:[0,1,1]
	v_lshlrev_b32_e32 v36, 16, v28
	v_and_b32_e32 v37, 0xffff0000, v28
	v_lshlrev_b32_e32 v28, 16, v27
	v_and_b32_e32 v29, 0xffff0000, v27
	v_pk_mul_f32 v[8:9], v[8:9], v[32:33] op_sel_hi:[1,0]
	s_addc_u32 s27, s25, s15
	v_pk_fma_f32 v[8:9], v[34:35], v[28:29], v[8:9] op_sel_hi:[0,1,1]
	v_readlane_b32 s100, v200, 25
	s_add_u32 s26, s34, s14
	s_addc_u32 s27, s36, s15
	v_readlane_b32 s101, v201, 25
	s_nop 1
	v_mov_b32_e32 v28, s100
	v_mov_b32_e32 v27, s101
	s_and_b32 s13, s16, 0x79
	v_pk_mul_f32 v[6:7], v[6:7], v[32:33] op_sel_hi:[1,0]
	s_mul_i32 s90, s13, 0x9000
	v_pk_fma_f32 v[6:7], v[34:35], v[36:37], v[6:7] op_sel_hi:[0,1,1]
	v_lshl_add_u64 v[32:33], v[0:1], 0, s[90:91]
	v_cvt_pk_bf16_f32 v29, v4, v5
	global_store_dword v[32:33], v29, off
	v_cvt_pk_bf16_f32 v29, v6, v7
	global_store_dword v[32:33], v29, off offset:1536
	v_cvt_pk_bf16_f32 v29, v8, v9
	global_store_dword v[32:33], v29, off offset:3072
	s_and_saveexec_b64 s[16:17], s[8:9]
	s_cbranch_execz .LBB0_419
	s_add_u32 s14, s37, s14
	s_addc_u32 s15, s40, s15
	global_store_dword v181, v30, s[14:15]
.LBB0_419:
	s_or_b64 exec, exec, s[16:17]
	s_nop 0
	v_add_f32_e32 v29, v30, v27
	v_max_f32_e32 v27, v28, v28
	v_max_f32_e32 v27, v29, v27
	v_sub_f32_e32 v29, v29, v27
	v_mul_f32_e32 v29, 0x3fb8aa3b, v29
	v_sub_f32_e32 v28, v28, v27
	v_exp_f32_e32 v30, v29
	v_mul_f32_e32 v28, 0x3fb8aa3b, v28
	s_or_b32 s16, s12, 26
	v_exp_f32_e32 v28, v28
	s_ashr_i32 s17, s16, 31
	s_lshl_b64 s[14:15], s[16:17], 2
	s_add_u32 s26, s67, s14
	v_lshlrev_b32_e32 v32, 16, v26
	v_pk_mul_f32 v[4:5], v[4:5], v[30:31] op_sel_hi:[1,0]
	v_and_b32_e32 v33, 0xffff0000, v26
	s_addc_u32 s27, s25, s15
	v_pk_fma_f32 v[4:5], v[28:29], v[32:33], v[4:5] op_sel_hi:[0,1,1]
	v_lshlrev_b32_e32 v32, 16, v25
	v_and_b32_e32 v33, 0xffff0000, v25
	v_readlane_b32 s100, v200, 26
	s_add_u32 s26, s34, s14
	v_pk_mul_f32 v[6:7], v[6:7], v[30:31] op_sel_hi:[1,0]
	s_addc_u32 s27, s36, s15
	v_pk_fma_f32 v[6:7], v[28:29], v[32:33], v[6:7] op_sel_hi:[0,1,1]
	v_lshlrev_b32_e32 v32, 16, v24
	v_and_b32_e32 v33, 0xffff0000, v24
	v_readlane_b32 s101, v201, 26
	s_nop 1
	v_mov_b32_e32 v25, s100
	v_mov_b32_e32 v24, s101
	s_and_b32 s13, s16, 0x7a
	v_pk_mul_f32 v[8:9], v[8:9], v[30:31] op_sel_hi:[1,0]
	s_mul_i32 s90, s13, 0x9000
	v_pk_fma_f32 v[8:9], v[28:29], v[32:33], v[8:9] op_sel_hi:[0,1,1]
	v_lshl_add_u64 v[28:29], v[0:1], 0, s[90:91]
	v_cvt_pk_bf16_f32 v26, v4, v5
	global_store_dword v[28:29], v26, off
	v_cvt_pk_bf16_f32 v26, v6, v7
	global_store_dword v[28:29], v26, off offset:1536
	v_cvt_pk_bf16_f32 v26, v8, v9
	global_store_dword v[28:29], v26, off offset:3072
	s_and_saveexec_b64 s[16:17], s[8:9]
	s_cbranch_execz .LBB0_421
	s_add_u32 s14, s37, s14
	s_addc_u32 s15, s40, s15
	global_store_dword v181, v27, s[14:15]
.LBB0_421:
	s_or_b64 exec, exec, s[16:17]
	s_nop 0
	v_add_f32_e32 v26, v27, v24
	v_max_f32_e32 v24, v25, v25
	v_max_f32_e32 v24, v26, v24
	v_sub_f32_e32 v26, v26, v24
	v_mul_f32_e32 v26, 0x3fb8aa3b, v26
	v_sub_f32_e32 v25, v25, v24
	v_exp_f32_e32 v26, v26
	v_mul_f32_e32 v25, 0x3fb8aa3b, v25
	v_exp_f32_e32 v28, v25
	s_or_b32 s14, s12, 27
	s_ashr_i32 s15, s14, 31
	s_lshl_b64 s[12:13], s[14:15], 2
	v_lshlrev_b32_e32 v30, 16, v23
	v_and_b32_e32 v31, 0xffff0000, v23
	v_pk_mul_f32 v[4:5], v[4:5], v[26:27] op_sel_hi:[1,0]
	s_add_u32 s16, s67, s12
	v_pk_fma_f32 v[4:5], v[28:29], v[30:31], v[4:5] op_sel_hi:[0,1,1]
	v_lshlrev_b32_e32 v30, 16, v22
	v_and_b32_e32 v31, 0xffff0000, v22
	v_lshlrev_b32_e32 v22, 16, v21
	v_and_b32_e32 v23, 0xffff0000, v21
	v_pk_mul_f32 v[8:9], v[8:9], v[26:27] op_sel_hi:[1,0]
	s_addc_u32 s17, s25, s13
	v_pk_fma_f32 v[8:9], v[28:29], v[22:23], v[8:9] op_sel_hi:[0,1,1]
	v_readlane_b32 s100, v200, 27
	s_add_u32 s16, s34, s12
	s_addc_u32 s17, s36, s13
	v_readlane_b32 s101, v201, 27
	s_nop 1
	v_mov_b32_e32 v22, s100
	v_mov_b32_e32 v21, s101
	s_and_b32 s14, s14, 0x7b
	v_pk_mul_f32 v[6:7], v[6:7], v[26:27] op_sel_hi:[1,0]
	s_mul_i32 s90, s14, 0x9000
	v_pk_fma_f32 v[6:7], v[28:29], v[30:31], v[6:7] op_sel_hi:[0,1,1]
	v_lshl_add_u64 v[26:27], v[0:1], 0, s[90:91]
	v_cvt_pk_bf16_f32 v23, v4, v5
	global_store_dword v[26:27], v23, off
	v_cvt_pk_bf16_f32 v23, v6, v7
	global_store_dword v[26:27], v23, off offset:1536
	v_cvt_pk_bf16_f32 v23, v8, v9
	global_store_dword v[26:27], v23, off offset:3072
	s_and_saveexec_b64 s[14:15], s[8:9]
	s_cbranch_execz .LBB0_423
	s_add_u32 s12, s37, s12
	s_addc_u32 s13, s40, s13
	global_store_dword v181, v24, s[12:13]
.LBB0_423:
	s_or_b64 exec, exec, s[14:15]
	s_nop 0
	v_add_f32_e32 v23, v24, v21
	v_max_f32_e32 v21, v22, v22
	v_max_f32_e32 v21, v23, v21
	v_sub_f32_e32 v23, v23, v21
	v_mul_f32_e32 v23, 0x3fb8aa3b, v23
	v_sub_f32_e32 v22, v22, v21
	v_exp_f32_e32 v24, v23
	v_mul_f32_e32 v22, 0x3fb8aa3b, v22
	s_or_b32 s14, s18, 28
	v_exp_f32_e32 v22, v22
	s_ashr_i32 s15, s14, 31
	s_lshl_b64 s[12:13], s[14:15], 2
	s_add_u32 s16, s67, s12
	v_lshlrev_b32_e32 v26, 16, v20
	v_and_b32_e32 v27, 0xffff0000, v20
	v_pk_mul_f32 v[4:5], v[4:5], v[24:25] op_sel_hi:[1,0]
	s_addc_u32 s17, s25, s13
	v_pk_fma_f32 v[4:5], v[22:23], v[26:27], v[4:5] op_sel_hi:[0,1,1]
	v_lshlrev_b32_e32 v26, 16, v19
	v_and_b32_e32 v27, 0xffff0000, v19
	v_readlane_b32 s100, v200, 28
	s_add_u32 s16, s34, s12
	v_pk_mul_f32 v[6:7], v[6:7], v[24:25] op_sel_hi:[1,0]
	s_addc_u32 s17, s36, s13
	v_pk_fma_f32 v[6:7], v[22:23], v[26:27], v[6:7] op_sel_hi:[0,1,1]
	v_lshlrev_b32_e32 v26, 16, v18
	v_and_b32_e32 v27, 0xffff0000, v18
	v_readlane_b32 s101, v201, 28
	s_nop 1
	v_mov_b32_e32 v19, s100
	v_mov_b32_e32 v18, s101
	s_and_b32 s14, s14, 0x7c
	v_pk_mul_f32 v[8:9], v[8:9], v[24:25] op_sel_hi:[1,0]
	s_mul_i32 s90, s14, 0x9000
	v_pk_fma_f32 v[8:9], v[22:23], v[26:27], v[8:9] op_sel_hi:[0,1,1]
	v_lshl_add_u64 v[22:23], v[0:1], 0, s[90:91]
	v_cvt_pk_bf16_f32 v20, v4, v5
	global_store_dword v[22:23], v20, off
	v_cvt_pk_bf16_f32 v20, v6, v7
	global_store_dword v[22:23], v20, off offset:1536
	v_cvt_pk_bf16_f32 v20, v8, v9
	global_store_dword v[22:23], v20, off offset:3072
	s_and_saveexec_b64 s[14:15], s[8:9]
	s_cbranch_execz .LBB0_425
	s_add_u32 s12, s37, s12
	s_addc_u32 s13, s40, s13
	global_store_dword v181, v21, s[12:13]
.LBB0_425:
	s_or_b64 exec, exec, s[14:15]
	s_nop 0
	v_add_f32_e32 v20, v21, v18
	v_max_f32_e32 v18, v19, v19
	v_max_f32_e32 v18, v20, v18
	v_sub_f32_e32 v20, v20, v18
	v_mul_f32_e32 v20, 0x3fb8aa3b, v20
	v_sub_f32_e32 v19, v19, v18
	v_exp_f32_e32 v20, v20
	v_mul_f32_e32 v19, 0x3fb8aa3b, v19
	v_exp_f32_e32 v22, v19
	s_or_b32 s14, s18, 29
	s_ashr_i32 s15, s14, 31
	v_lshlrev_b32_e32 v24, 16, v17
	v_and_b32_e32 v25, 0xffff0000, v17
	v_pk_mul_f32 v[4:5], v[4:5], v[20:21] op_sel_hi:[1,0]
	s_lshl_b64 s[12:13], s[14:15], 2
	v_pk_fma_f32 v[4:5], v[22:23], v[24:25], v[4:5] op_sel_hi:[0,1,1]
	v_lshlrev_b32_e32 v24, 16, v11
	v_and_b32_e32 v25, 0xffff0000, v11
	v_pk_mul_f32 v[6:7], v[6:7], v[20:21] op_sel_hi:[1,0]
	s_add_u32 s16, s67, s12
	v_pk_fma_f32 v[6:7], v[22:23], v[24:25], v[6:7] op_sel_hi:[0,1,1]
	v_lshlrev_b32_e32 v24, 16, v10
	v_and_b32_e32 v25, 0xffff0000, v10
	v_pk_mul_f32 v[8:9], v[8:9], v[20:21] op_sel_hi:[1,0]
	s_addc_u32 s17, s25, s13
	v_pk_fma_f32 v[10:11], v[22:23], v[24:25], v[8:9] op_sel_hi:[0,1,1]
	v_readlane_b32 s100, v200, 29
	s_add_u32 s16, s34, s12
	s_addc_u32 s17, s36, s13
	v_readlane_b32 s101, v201, 29
	s_nop 1
	v_mov_b32_e32 v8, s100
	v_mov_b32_e32 v9, s101
	s_and_b32 s14, s14, 0x7d
	s_mul_i32 s90, s14, 0x9000
	v_lshl_add_u64 v[20:21], v[0:1], 0, s[90:91]
	v_cvt_pk_bf16_f32 v17, v4, v5
	global_store_dword v[20:21], v17, off
	v_cvt_pk_bf16_f32 v17, v6, v7
	global_store_dword v[20:21], v17, off offset:1536
	v_cvt_pk_bf16_f32 v17, v10, v11
	global_store_dword v[20:21], v17, off offset:3072
	s_and_saveexec_b64 s[14:15], s[8:9]
	s_cbranch_execz .LBB0_427
	s_add_u32 s12, s37, s12
	s_addc_u32 s13, s40, s13
	global_store_dword v181, v18, s[12:13]
.LBB0_427:
	s_or_b64 exec, exec, s[14:15]
	s_nop 0
	v_add_f32_e32 v9, v18, v9
	v_max_f32_e32 v17, v8, v8
	v_max_f32_e32 v17, v9, v17
	v_sub_f32_e32 v9, v9, v17
	v_mul_f32_e32 v9, 0x3fb8aa3b, v9
	v_sub_f32_e32 v8, v8, v17
	v_exp_f32_e32 v18, v9
	v_mul_f32_e32 v8, 0x3fb8aa3b, v8
	v_exp_f32_e32 v20, v8
	s_or_b32 s14, s18, 30
	s_ashr_i32 s15, s14, 31
	v_lshlrev_b32_e32 v8, 16, v16
	v_and_b32_e32 v9, 0xffff0000, v16
	v_pk_mul_f32 v[4:5], v[4:5], v[18:19] op_sel_hi:[1,0]
	s_lshl_b64 s[12:13], s[14:15], 2
	v_pk_fma_f32 v[8:9], v[20:21], v[8:9], v[4:5] op_sel_hi:[0,1,1]
	v_lshlrev_b32_e32 v4, 16, v15
	v_and_b32_e32 v5, 0xffff0000, v15
	v_pk_mul_f32 v[6:7], v[6:7], v[18:19] op_sel_hi:[1,0]
	s_add_u32 s16, s67, s12
	v_pk_fma_f32 v[6:7], v[20:21], v[4:5], v[6:7] op_sel_hi:[0,1,1]
	v_lshlrev_b32_e32 v4, 16, v14
	v_and_b32_e32 v5, 0xffff0000, v14
	v_pk_mul_f32 v[10:11], v[10:11], v[18:19] op_sel_hi:[1,0]
	s_addc_u32 s17, s25, s13
	v_pk_fma_f32 v[4:5], v[20:21], v[4:5], v[10:11] op_sel_hi:[0,1,1]
	v_readlane_b32 s100, v200, 30
	s_add_u32 s16, s34, s12
	s_addc_u32 s17, s36, s13
	v_readlane_b32 s101, v201, 30
	s_nop 1
	v_mov_b32_e32 v10, s100
	v_mov_b32_e32 v11, s101
	s_and_b32 s14, s14, 0x7e
	s_mul_i32 s90, s14, 0x9000
	v_lshl_add_u64 v[14:15], v[0:1], 0, s[90:91]
	v_cvt_pk_bf16_f32 v16, v8, v9
	global_store_dword v[14:15], v16, off
	v_cvt_pk_bf16_f32 v16, v6, v7
	global_store_dword v[14:15], v16, off offset:1536
	v_cvt_pk_bf16_f32 v16, v4, v5
	global_store_dword v[14:15], v16, off offset:3072
	s_and_saveexec_b64 s[14:15], s[8:9]
	s_cbranch_execz .LBB0_429
	s_add_u32 s12, s37, s12
	s_addc_u32 s13, s40, s13
	global_store_dword v181, v17, s[12:13]
.LBB0_429:
	s_or_b64 exec, exec, s[14:15]
	s_nop 0
	v_add_f32_e32 v14, v17, v11
	v_max_f32_e32 v11, v10, v10
	v_max_f32_e32 v11, v14, v11
	v_sub_f32_e32 v14, v14, v11
	v_mul_f32_e32 v14, 0x3fb8aa3b, v14
	v_sub_f32_e32 v10, v10, v11
	v_exp_f32_e32 v14, v14
	v_mul_f32_e32 v10, 0x3fb8aa3b, v10
	v_exp_f32_e32 v10, v10
	s_or_b32 s12, s18, 31
	v_lshlrev_b32_e32 v16, 16, v13
	v_and_b32_e32 v17, 0xffff0000, v13
	v_pk_mul_f32 v[8:9], v[8:9], v[14:15] op_sel_hi:[1,0]
	s_and_b32 s13, s12, 0x7f
	v_pk_fma_f32 v[8:9], v[10:11], v[16:17], v[8:9] op_sel_hi:[0,1,1]
	v_lshlrev_b32_e32 v16, 16, v12
	v_and_b32_e32 v17, 0xffff0000, v12
	v_pk_mul_f32 v[6:7], v[6:7], v[14:15] op_sel_hi:[1,0]
	s_mul_i32 s90, s13, 0x9000
	v_pk_fma_f32 v[6:7], v[10:11], v[16:17], v[6:7] op_sel_hi:[0,1,1]
	v_lshlrev_b32_e32 v12, 16, v3
	v_and_b32_e32 v13, 0xffff0000, v3
	v_pk_mul_f32 v[4:5], v[4:5], v[14:15] op_sel_hi:[1,0]
	v_lshl_add_u64 v[0:1], v[0:1], 0, s[90:91]
	v_cvt_pk_bf16_f32 v3, v8, v9
	v_pk_fma_f32 v[4:5], v[10:11], v[12:13], v[4:5] op_sel_hi:[0,1,1]
	global_store_dword v[0:1], v3, off
	v_cvt_pk_bf16_f32 v3, v6, v7
	global_store_dword v[0:1], v3, off offset:1536
	v_cvt_pk_bf16_f32 v3, v4, v5
	global_store_dword v[0:1], v3, off offset:3072
	s_and_b64 exec, exec, s[8:9]
	s_cbranch_execz .LBB0_365
	s_ashr_i32 s13, s12, 31
	s_lshl_b64 s[8:9], s[12:13], 2
	s_add_u32 s8, s37, s8
	s_addc_u32 s9, s40, s9
	global_store_dword v181, v11, s[8:9]
	s_branch .LBB0_365
